# first-k-iteration-peeled-c0-no-accumulator-zeroing
# speedup vs baseline: 1.0088x; 1.0068x over previous
; #define PG8_STAGE(bufoff, gbase, hoff, imm) do { _Pragma("unroll") for (int _i = 0; _i < 2; ++_i) { \
;         asm volatile("s_mov_b32 m0, %0\n\ts_nop 0\n\tglobal_load_lds_dwordx4 %1, %2" \
;             :: "s"(lds0 + (unsigned)((bufoff) + _i * 8192)), "v"(voff0), "s"((const char*)(gbase) + (size_t)(hoff) + (size_t)(_i * 8192)) : "memory"); } } while (0)
; #define PG8_LDA(dst, b, h) do { _Pragma("unroll") for (int m = 0; m < 4; ++m) _Pragma("unroll") for (int k = 0; k < 2; ++k) dst[m][k] = *(const LAS bf16x8*)(lds + PG8_SA(b, h) + aoff + m * 2048 + k * 1024); } while (0)
; #define PG8_LDB(dst, b, h) do { _Pragma("unroll") for (int n = 0; n < 2; ++n) _Pragma("unroll") for (int k = 0; k < 2; ++k) dst[n][k] = *(const LAS bf16x8*)(lds + PG8_SB(b, h) + boff + n * 2048 + k * 1024); } while (0)
; #define PG8_WAIT_V(n) asm volatile("s_waitcnt vmcnt(" #n ")" ::: "memory")
; #define PG8_WAIT_L(n) asm volatile("s_waitcnt lgkmcnt(" #n ")" ::: "memory")
; #define PG8_BAR __builtin_amdgcn_s_barrier()
; template <class Epi>
; __device__ __forceinline__ void gemm_phase(LAS unsigned char* lds, const Gemm g, const StaticOrder& S, const Epi& E) {
;     ...
;         const bool has_next = S.next(ui + 1, nxt);
;         const char* nA = has_next ? (const char*)g.A + (size_t)nxt.pm * tstepA + (size_t)(nxt.pn >> g.gshift) * g.gstride : cA;
;         const char* nB = has_next ? (const char*)g.Bt + (size_t)nxt.pn * tstepB : cB;
;         for (int t = 0; t < nt; t += 2) {
;             const bool last = (t == nt - 2);
;             if (last) E.pre(cur, wid, lane, (unsigned)(size_t)(lds + STAGE_BYTES));
;             const char* aT = cA + (size_t)t * KS;
;             const char* a2 = last ? nA : aT + 2 * KS; const char* b2 = last ? nB : cB + (size_t)(t + 2) * KS;
;             PG8_LDB(B0, 0, 0); PG8_SCHED; PG8_LDA(At, 0, 0); PG8_STAGE(PG8_SA(1, 1), aT + KS, hA, 0);
;             PG8_WAIT_L(8); PG8_BAR; PG8_WAIT_L(0); PG8_MMA(0, 0, At, B0); PG8_BAR; PG8_SCHED;
;             PG8_LDB(B1, 0, 1); PG8_STAGE(PG8_SB(0, 0), b2, 0, 0);
;             PG8_BAR; PG8_WAIT_L(0); PG8_MMA(0, 1, At, B1); PG8_BAR;
;             PG8_LDA(At, 0, 1); PG8_STAGE(PG8_SA(0, 0), a2, 0, 0);
;             PG8_BAR; PG8_WAIT_L(0); PG8_MMA(1, 0, At, B0); PG8_BAR; PG8_SCHED;
;             PG8_STAGE(PG8_SB(0, 1), b2, hB, 0);
;             PG8_WAIT_V(6); PG8_BAR; PG8_MMA(1, 1, At, B1); PG8_BAR;
.LBB0_292:
	s_ashr_i32 s47, s46, 31
	s_lshl_b64 s[0:1], s[46:47], 20
	s_add_u32 s45, s57, s0
	s_addc_u32 s47, s58, s1
	s_ashr_i32 s0, s44, 1
	s_ashr_i32 s1, s0, 31
	s_lshl_b64 s[0:1], s[0:1], 17
	v_cmp_lt_i64_e32 vcc, s[48:49], v[194:195]
	s_add_u32 s48, s45, s0
	s_addc_u32 s49, s47, s1
	s_and_b64 s[0:1], vcc, exec
	s_cselect_b32 s0, s49, s9
	s_cselect_b32 s1, s48, s8
	s_ashr_i32 s45, s44, 31
	s_lshl_b64 s[50:51], s[44:45], 18
	s_add_u32 s50, s34, s50
	s_addc_u32 s51, s35, s51
	s_and_b64 s[54:55], vcc, exec
	s_cselect_b32 s45, s51, s53
	s_cselect_b32 s47, s50, s52
	s_add_u32 s93, s52, 0x8000
	s_addc_u32 s94, s53, 0
	s_mov_b32 s95, -2
	s_waitcnt vmcnt(8)
	s_add_u32 s52, s8, 0x8000
	s_addc_u32 s53, s9, 0
	ds_read_b128 v[128:131], v224
	ds_read_b128 v[132:135], v224 offset:1024
	ds_read_b128 v[136:139], v224 offset:2048
	ds_read_b128 v[140:143], v224 offset:3072
	s_add_u32 s54, s8, 0x84000
	s_addc_u32 s55, s9, 0
	s_add_u32 s96, s8, 0x86000
	s_addc_u32 s97, s9, 0
	s_cmp_eq_u32 s95, 4
	s_cselect_b32 s9, s0, s53
	s_cselect_b32 s8, s1, s52
	ds_read_b128 v[144:147], v225
	ds_read_b128 v[148:151], v225 offset:1024
	ds_read_b128 v[152:155], v225 offset:2048
	ds_read_b128 v[156:159], v225 offset:3072
	ds_read_b128 v[160:163], v225 offset:4096
	ds_read_b128 v[164:167], v225 offset:5120
	ds_read_b128 v[168:171], v225 offset:6144
	ds_read_b128 v[172:175], v225 offset:7168
	s_mov_b32 m0, s86
	s_nop 0
	global_load_lds_dwordx4 v221, s[54:55]
	s_mov_b32 m0, s87
	s_nop 0
	global_load_lds_dwordx4 v221, s[96:97]
	s_waitcnt lgkmcnt(8)
	s_waitcnt vmcnt(10)
	s_barrier
	s_waitcnt lgkmcnt(7)
	v_mfma_f32_16x16x32_bf16 v[124:127], v[128:131], v[144:147], 0
	v_mfma_f32_16x16x32_bf16 v[120:123], v[136:139], v[144:147], 0
	s_waitcnt lgkmcnt(5)
	v_mfma_f32_16x16x32_bf16 v[116:119], v[128:131], v[152:155], 0
	v_mfma_f32_16x16x32_bf16 v[112:115], v[136:139], v[152:155], 0
	s_waitcnt lgkmcnt(3)
	v_mfma_f32_16x16x32_bf16 v[96:99], v[128:131], v[160:163], 0
	v_mfma_f32_16x16x32_bf16 v[88:91], v[136:139], v[160:163], 0
	s_waitcnt lgkmcnt(1)
	v_mfma_f32_16x16x32_bf16 v[80:83], v[128:131], v[168:171], 0
	v_mfma_f32_16x16x32_bf16 v[72:75], v[136:139], v[168:171], 0
	v_mfma_f32_16x16x32_bf16 v[124:127], v[132:135], v[148:151], v[124:127]
	v_mfma_f32_16x16x32_bf16 v[120:123], v[140:143], v[148:151], v[120:123]
	v_mfma_f32_16x16x32_bf16 v[116:119], v[132:135], v[156:159], v[116:119]
	v_mfma_f32_16x16x32_bf16 v[112:115], v[140:143], v[156:159], v[112:115]
	v_mfma_f32_16x16x32_bf16 v[96:99], v[132:135], v[164:167], v[96:99]
	v_mfma_f32_16x16x32_bf16 v[88:91], v[140:143], v[164:167], v[88:91]
	s_waitcnt lgkmcnt(0)
	v_mfma_f32_16x16x32_bf16 v[80:83], v[132:135], v[172:175], v[80:83]
	v_mfma_f32_16x16x32_bf16 v[72:75], v[140:143], v[172:175], v[72:75]
	s_barrier
	ds_read_b128 v[176:179], v226
	ds_read_b128 v[180:183], v226 offset:1024
	ds_read_b128 v[184:187], v226 offset:2048
	ds_read_b128 v[188:191], v226 offset:3072
	s_cselect_b32 s54, s47, s93
	s_cselect_b32 s55, s45, s94
	s_mov_b32 m0, s60
	s_nop 0
	global_load_lds_dwordx4 v221, s[54:55]
	s_add_u32 s96, s54, 0x2000
	s_addc_u32 s97, s55, 0
	s_mov_b32 m0, s61
	s_nop 0
	global_load_lds_dwordx4 v221, s[96:97]
	s_waitcnt vmcnt(10)
	s_barrier
	s_waitcnt lgkmcnt(3)
	v_mfma_f32_16x16x32_bf16 v[108:111], v[176:179], v[144:147], 0
	s_waitcnt lgkmcnt(1)
	v_mfma_f32_16x16x32_bf16 v[104:107], v[184:187], v[144:147], 0
	v_mfma_f32_16x16x32_bf16 v[100:103], v[176:179], v[152:155], 0
	v_mfma_f32_16x16x32_bf16 v[92:95], v[184:187], v[152:155], 0
	v_mfma_f32_16x16x32_bf16 v[84:87], v[176:179], v[160:163], 0
	v_mfma_f32_16x16x32_bf16 v[76:79], v[184:187], v[160:163], 0
	v_mfma_f32_16x16x32_bf16 v[68:71], v[176:179], v[168:171], 0
	v_mfma_f32_16x16x32_bf16 v[64:67], v[184:187], v[168:171], 0
	v_mfma_f32_16x16x32_bf16 v[108:111], v[180:183], v[148:151], v[108:111]
	s_waitcnt lgkmcnt(0)
	v_mfma_f32_16x16x32_bf16 v[104:107], v[188:191], v[148:151], v[104:107]
	v_mfma_f32_16x16x32_bf16 v[100:103], v[180:183], v[156:159], v[100:103]
	v_mfma_f32_16x16x32_bf16 v[92:95], v[188:191], v[156:159], v[92:95]
	v_mfma_f32_16x16x32_bf16 v[84:87], v[180:183], v[164:167], v[84:87]
	v_mfma_f32_16x16x32_bf16 v[76:79], v[188:191], v[164:167], v[76:79]
	v_mfma_f32_16x16x32_bf16 v[68:71], v[180:183], v[172:175], v[68:71]
	v_mfma_f32_16x16x32_bf16 v[64:67], v[188:191], v[172:175], v[64:67]
	s_barrier
	ds_read_b128 v[144:147], v225 offset:16384
	ds_read_b128 v[148:151], v225 offset:17408
	ds_read_b128 v[152:155], v225 offset:18432
	ds_read_b128 v[156:159], v225 offset:19456
	ds_read_b128 v[160:163], v225 offset:20480
	ds_read_b128 v[164:167], v225 offset:21504
	ds_read_b128 v[168:171], v225 offset:22528
	ds_read_b128 v[172:175], v225 offset:23552
	s_mov_b32 m0, s59
	s_nop 0
	global_load_lds_dwordx4 v221, s[8:9]
	s_add_u32 s96, s8, 0x2000
	s_addc_u32 s97, s9, 0
	s_mov_b32 m0, s62
	s_nop 0
	global_load_lds_dwordx4 v221, s[96:97]
	s_barrier
	s_waitcnt lgkmcnt(7)
	v_mfma_f32_16x16x32_bf16 v[60:63], v[128:131], v[144:147], 0
	v_mfma_f32_16x16x32_bf16 v[56:59], v[136:139], v[144:147], 0
	s_waitcnt lgkmcnt(5)
	v_mfma_f32_16x16x32_bf16 v[48:51], v[128:131], v[152:155], 0
	v_mfma_f32_16x16x32_bf16 v[40:43], v[136:139], v[152:155], 0
	s_waitcnt lgkmcnt(3)
	v_mfma_f32_16x16x32_bf16 v[32:35], v[128:131], v[160:163], 0
	v_mfma_f32_16x16x32_bf16 v[24:27], v[136:139], v[160:163], 0
	s_waitcnt lgkmcnt(1)
	v_mfma_f32_16x16x32_bf16 v[16:19], v[128:131], v[168:171], 0
	v_mfma_f32_16x16x32_bf16 v[8:11], v[136:139], v[168:171], 0
	v_mfma_f32_16x16x32_bf16 v[60:63], v[132:135], v[148:151], v[60:63]
	v_mfma_f32_16x16x32_bf16 v[56:59], v[140:143], v[148:151], v[56:59]
	v_mfma_f32_16x16x32_bf16 v[48:51], v[132:135], v[156:159], v[48:51]
	v_mfma_f32_16x16x32_bf16 v[40:43], v[140:143], v[156:159], v[40:43]
	v_mfma_f32_16x16x32_bf16 v[32:35], v[132:135], v[164:167], v[32:35]
	v_mfma_f32_16x16x32_bf16 v[24:27], v[140:143], v[164:167], v[24:27]
	s_waitcnt lgkmcnt(0)
	v_mfma_f32_16x16x32_bf16 v[16:19], v[132:135], v[172:175], v[16:19]
	v_mfma_f32_16x16x32_bf16 v[8:11], v[140:143], v[172:175], v[8:11]
	s_barrier
; #define PG8_STAGE(bufoff, gbase, hoff, imm) do { _Pragma("unroll") for (int _i = 0; _i < 2; ++_i) { \
;         asm volatile("s_mov_b32 m0, %0\n\ts_nop 0\n\tglobal_load_lds_dwordx4 %1, %2" \
;             :: "s"(lds0 + (unsigned)((bufoff) + _i * 8192)), "v"(voff0), "s"((const char*)(gbase) + (size_t)(hoff) + (size_t)(_i * 8192)) : "memory"); } } while (0)
; #define PG8_LDA(dst, b, h) do { _Pragma("unroll") for (int m = 0; m < 4; ++m) _Pragma("unroll") for (int k = 0; k < 2; ++k) dst[m][k] = *(const LAS bf16x8*)(lds + PG8_SA(b, h) + aoff + m * 2048 + k * 1024); } while (0)
; #define PG8_LDB(dst, b, h) do { _Pragma("unroll") for (int n = 0; n < 2; ++n) _Pragma("unroll") for (int k = 0; k < 2; ++k) dst[n][k] = *(const LAS bf16x8*)(lds + PG8_SB(b, h) + boff + n * 2048 + k * 1024); } while (0)
; #define PG8_MMA(ai, bj, At, Bt) do { __builtin_amdgcn_s_setprio(1); _Pragma("unroll") for (int m = 0; m < 4; ++m) _Pragma("unroll") for (int n = 0; n < 2; ++n) _Pragma("unroll") for (int k = 0; k < 2; ++k) \
;         acc[ai][bj][m][n] = __builtin_amdgcn_mfma_f32_16x16x32_bf16(Bt[n][k], At[m][k], acc[ai][bj][m][n], 0, 0, 0); __builtin_amdgcn_s_setprio(0); } while (0)
; #define PG8_WAIT_V(n) asm volatile("s_waitcnt vmcnt(" #n ")" ::: "memory")
; #define PG8_WAIT_L(n) asm volatile("s_waitcnt lgkmcnt(" #n ")" ::: "memory")
; #define PG8_BAR __builtin_amdgcn_s_barrier()
; #define PG8_SCHED __builtin_amdgcn_sched_barrier(0)
; template <class Epi>
; __device__ __forceinline__ void gemm_phase(LAS unsigned char* lds, const Gemm g, const StaticOrder& S, const Epi& E) {
;     ...
;             PG8_STAGE(PG8_SB(0, 1), b2, hB, 0);
;             PG8_WAIT_V(6); PG8_BAR; PG8_MMA(1, 1, At, B1); PG8_BAR;
;             PG8_LDB(B0, 1, 0); PG8_SCHED; PG8_LDA(At, 1, 0); PG8_STAGE(PG8_SA(0, 1), a2, hA, 0);
;             PG8_WAIT_L(8); PG8_BAR; PG8_WAIT_L(0); PG8_MMA(0, 0, At, B0); PG8_BAR; PG8_SCHED;
;             PG8_LDB(B1, 1, 1); PG8_STAGE(PG8_SB(1, 0), b2 + KS, 0, 0);
;             PG8_BAR; PG8_WAIT_L(0); PG8_MMA(0, 1, At, B1); PG8_BAR;
;             PG8_LDA(At, 1, 1); PG8_STAGE(PG8_SA(1, 0), a2 + KS, 0, 0);
	s_add_u32 s96, s54, 0x20000
	s_addc_u32 s97, s55, 0
	s_mov_b32 m0, s63
	s_nop 0
	global_load_lds_dwordx4 v221, s[96:97]
	s_add_u32 s96, s54, 0x22000
	s_addc_u32 s97, s55, 0
	s_mov_b32 m0, s64
	s_nop 0
	global_load_lds_dwordx4 v221, s[96:97]
	s_waitcnt vmcnt(10)
	s_barrier
	v_mfma_f32_16x16x32_bf16 v[52:55], v[176:179], v[144:147], 0
	v_mfma_f32_16x16x32_bf16 v[44:47], v[184:187], v[144:147], 0
	v_mfma_f32_16x16x32_bf16 v[36:39], v[176:179], v[152:155], 0
	v_mfma_f32_16x16x32_bf16 v[28:31], v[184:187], v[152:155], 0
	v_mfma_f32_16x16x32_bf16 v[20:23], v[176:179], v[160:163], 0
	v_mfma_f32_16x16x32_bf16 v[12:15], v[184:187], v[160:163], 0
	v_mfma_f32_16x16x32_bf16 v[4:7], v[176:179], v[168:171], 0
	v_mfma_f32_16x16x32_bf16 v[0:3], v[184:187], v[168:171], 0
	v_mfma_f32_16x16x32_bf16 v[52:55], v[180:183], v[148:151], v[52:55]
	v_mfma_f32_16x16x32_bf16 v[44:47], v[188:191], v[148:151], v[44:47]
	v_mfma_f32_16x16x32_bf16 v[36:39], v[180:183], v[156:159], v[36:39]
	v_mfma_f32_16x16x32_bf16 v[28:31], v[188:191], v[156:159], v[28:31]
	v_mfma_f32_16x16x32_bf16 v[20:23], v[180:183], v[164:167], v[20:23]
	v_mfma_f32_16x16x32_bf16 v[12:15], v[188:191], v[164:167], v[12:15]
	v_mfma_f32_16x16x32_bf16 v[4:7], v[180:183], v[172:175], v[4:7]
	v_mfma_f32_16x16x32_bf16 v[0:3], v[188:191], v[172:175], v[0:3]
	s_barrier
	ds_read_b128 v[128:131], v227
	ds_read_b128 v[132:135], v227 offset:1024
	ds_read_b128 v[136:139], v227 offset:2048
	ds_read_b128 v[140:143], v227 offset:3072
	ds_read_b128 v[144:147], v225 offset:32768
	ds_read_b128 v[148:151], v225 offset:33792
	ds_read_b128 v[152:155], v225 offset:34816
	ds_read_b128 v[156:159], v225 offset:35840
	ds_read_b128 v[160:163], v225 offset:36864
	ds_read_b128 v[164:167], v225 offset:37888
	ds_read_b128 v[168:171], v225 offset:38912
	ds_read_b128 v[172:175], v225 offset:39936
	s_add_u32 s96, s8, 0x80000
	s_addc_u32 s97, s9, 0
	s_mov_b32 m0, s65
	s_nop 0
	global_load_lds_dwordx4 v221, s[96:97]
	s_add_u32 s96, s8, 0x82000
	s_addc_u32 s97, s9, 0
	s_mov_b32 m0, s66
	s_nop 0
	global_load_lds_dwordx4 v221, s[96:97]
	s_waitcnt lgkmcnt(8)
	s_waitcnt vmcnt(10)
	s_barrier
	s_waitcnt lgkmcnt(7)
	v_mfma_f32_16x16x32_bf16 v[124:127], v[128:131], v[144:147], v[124:127]
	v_mfma_f32_16x16x32_bf16 v[120:123], v[136:139], v[144:147], v[120:123]
	s_waitcnt lgkmcnt(5)
	v_mfma_f32_16x16x32_bf16 v[116:119], v[128:131], v[152:155], v[116:119]
	v_mfma_f32_16x16x32_bf16 v[112:115], v[136:139], v[152:155], v[112:115]
	s_waitcnt lgkmcnt(3)
	v_mfma_f32_16x16x32_bf16 v[96:99], v[128:131], v[160:163], v[96:99]
	v_mfma_f32_16x16x32_bf16 v[88:91], v[136:139], v[160:163], v[88:91]
	s_waitcnt lgkmcnt(1)
	v_mfma_f32_16x16x32_bf16 v[80:83], v[128:131], v[168:171], v[80:83]
	v_mfma_f32_16x16x32_bf16 v[72:75], v[136:139], v[168:171], v[72:75]
	v_mfma_f32_16x16x32_bf16 v[124:127], v[132:135], v[148:151], v[124:127]
	v_mfma_f32_16x16x32_bf16 v[120:123], v[140:143], v[148:151], v[120:123]
	v_mfma_f32_16x16x32_bf16 v[116:119], v[132:135], v[156:159], v[116:119]
	v_mfma_f32_16x16x32_bf16 v[112:115], v[140:143], v[156:159], v[112:115]
	v_mfma_f32_16x16x32_bf16 v[96:99], v[132:135], v[164:167], v[96:99]
	v_mfma_f32_16x16x32_bf16 v[88:91], v[140:143], v[164:167], v[88:91]
	s_waitcnt lgkmcnt(0)
	v_mfma_f32_16x16x32_bf16 v[80:83], v[132:135], v[172:175], v[80:83]
	v_mfma_f32_16x16x32_bf16 v[72:75], v[140:143], v[172:175], v[72:75]
	s_barrier
	ds_read_b128 v[176:179], v228
	ds_read_b128 v[180:183], v228 offset:1024
	ds_read_b128 v[184:187], v228 offset:2048
	ds_read_b128 v[188:191], v228 offset:3072
	s_add_u32 s96, s54, 0x4000
	s_addc_u32 s97, s55, 0
	s_mov_b32 m0, s69
	s_nop 0
	global_load_lds_dwordx4 v221, s[96:97]
	s_add_u32 s96, s54, 0x6000
	s_addc_u32 s97, s55, 0
	s_mov_b32 m0, s70
	s_nop 0
	global_load_lds_dwordx4 v221, s[96:97]
	s_waitcnt vmcnt(10)
	s_barrier
; #define PG8_STAGE(bufoff, gbase, hoff, imm) do { _Pragma("unroll") for (int _i = 0; _i < 2; ++_i) { \
;         asm volatile("s_mov_b32 m0, %0\n\ts_nop 0\n\tglobal_load_lds_dwordx4 %1, %2" \
;             :: "s"(lds0 + (unsigned)((bufoff) + _i * 8192)), "v"(voff0), "s"((const char*)(gbase) + (size_t)(hoff) + (size_t)(_i * 8192)) : "memory"); } } while (0)
; #define PG8_LDA(dst, b, h) do { _Pragma("unroll") for (int m = 0; m < 4; ++m) _Pragma("unroll") for (int k = 0; k < 2; ++k) dst[m][k] = *(const LAS bf16x8*)(lds + PG8_SA(b, h) + aoff + m * 2048 + k * 1024); } while (0)
; #define PG8_MMA(ai, bj, At, Bt) do { __builtin_amdgcn_s_setprio(1); _Pragma("unroll") for (int m = 0; m < 4; ++m) _Pragma("unroll") for (int n = 0; n < 2; ++n) _Pragma("unroll") for (int k = 0; k < 2; ++k) \
;         acc[ai][bj][m][n] = __builtin_amdgcn_mfma_f32_16x16x32_bf16(Bt[n][k], At[m][k], acc[ai][bj][m][n], 0, 0, 0); __builtin_amdgcn_s_setprio(0); } while (0)
; #define PG8_WAIT_V(n) asm volatile("s_waitcnt vmcnt(" #n ")" ::: "memory")
; #define PG8_WAIT_L(n) asm volatile("s_waitcnt lgkmcnt(" #n ")" ::: "memory")
; #define PG8_BAR __builtin_amdgcn_s_barrier()
; #define PG8_SCHED __builtin_amdgcn_sched_barrier(0)
; template <class Epi>
; __device__ __forceinline__ void gemm_phase(LAS unsigned char* lds, const Gemm g, const StaticOrder& S, const Epi& E) {
;     ...
;             PG8_LDA(At, 1, 1); PG8_STAGE(PG8_SA(1, 0), a2 + KS, 0, 0);
;             PG8_BAR; PG8_WAIT_L(0); PG8_MMA(1, 0, At, B0); PG8_BAR; PG8_SCHED;
;             PG8_STAGE(PG8_SB(1, 1), b2 + KS, hB, 0);
;             PG8_WAIT_V(6); PG8_BAR; PG8_MMA(1, 1, At, B1); PG8_BAR;
	s_waitcnt lgkmcnt(3)
	v_mfma_f32_16x16x32_bf16 v[108:111], v[176:179], v[144:147], v[108:111]
	s_waitcnt lgkmcnt(1)
	v_mfma_f32_16x16x32_bf16 v[104:107], v[184:187], v[144:147], v[104:107]
	v_mfma_f32_16x16x32_bf16 v[100:103], v[176:179], v[152:155], v[100:103]
	v_mfma_f32_16x16x32_bf16 v[92:95], v[184:187], v[152:155], v[92:95]
	v_mfma_f32_16x16x32_bf16 v[84:87], v[176:179], v[160:163], v[84:87]
	v_mfma_f32_16x16x32_bf16 v[76:79], v[184:187], v[160:163], v[76:79]
	v_mfma_f32_16x16x32_bf16 v[68:71], v[176:179], v[168:171], v[68:71]
	v_mfma_f32_16x16x32_bf16 v[64:67], v[184:187], v[168:171], v[64:67]
	v_mfma_f32_16x16x32_bf16 v[108:111], v[180:183], v[148:151], v[108:111]
	s_waitcnt lgkmcnt(0)
	v_mfma_f32_16x16x32_bf16 v[104:107], v[188:191], v[148:151], v[104:107]
	v_mfma_f32_16x16x32_bf16 v[100:103], v[180:183], v[156:159], v[100:103]
	v_mfma_f32_16x16x32_bf16 v[92:95], v[188:191], v[156:159], v[92:95]
	v_mfma_f32_16x16x32_bf16 v[84:87], v[180:183], v[164:167], v[84:87]
	v_mfma_f32_16x16x32_bf16 v[76:79], v[188:191], v[164:167], v[76:79]
	v_mfma_f32_16x16x32_bf16 v[68:71], v[180:183], v[172:175], v[68:71]
	v_mfma_f32_16x16x32_bf16 v[64:67], v[188:191], v[172:175], v[64:67]
	s_barrier
	ds_read_b128 v[144:147], v225 offset:49152
	ds_read_b128 v[148:151], v225 offset:50176
	ds_read_b128 v[152:155], v225 offset:51200
	ds_read_b128 v[156:159], v225 offset:52224
	ds_read_b128 v[160:163], v225 offset:53248
	ds_read_b128 v[164:167], v225 offset:54272
	ds_read_b128 v[168:171], v225 offset:55296
	ds_read_b128 v[172:175], v225 offset:56320
	s_add_u32 s96, s8, 0x4000
	s_addc_u32 s97, s9, 0
	s_mov_b32 m0, s71
	s_nop 0
	global_load_lds_dwordx4 v221, s[96:97]
	s_add_u32 s8, s8, 0x6000
	s_addc_u32 s9, s9, 0
	s_mov_b32 m0, s72
	s_nop 0
	global_load_lds_dwordx4 v221, s[8:9]
	s_barrier
	s_waitcnt lgkmcnt(7)
	v_mfma_f32_16x16x32_bf16 v[60:63], v[128:131], v[144:147], v[60:63]
	v_mfma_f32_16x16x32_bf16 v[56:59], v[136:139], v[144:147], v[56:59]
	s_waitcnt lgkmcnt(5)
	v_mfma_f32_16x16x32_bf16 v[48:51], v[128:131], v[152:155], v[48:51]
	v_mfma_f32_16x16x32_bf16 v[40:43], v[136:139], v[152:155], v[40:43]
	s_waitcnt lgkmcnt(3)
	v_mfma_f32_16x16x32_bf16 v[32:35], v[128:131], v[160:163], v[32:35]
	v_mfma_f32_16x16x32_bf16 v[24:27], v[136:139], v[160:163], v[24:27]
	s_waitcnt lgkmcnt(1)
	v_mfma_f32_16x16x32_bf16 v[16:19], v[128:131], v[168:171], v[16:19]
	v_mfma_f32_16x16x32_bf16 v[8:11], v[136:139], v[168:171], v[8:11]
	v_mfma_f32_16x16x32_bf16 v[60:63], v[132:135], v[148:151], v[60:63]
	v_mfma_f32_16x16x32_bf16 v[56:59], v[140:143], v[148:151], v[56:59]
	v_mfma_f32_16x16x32_bf16 v[48:51], v[132:135], v[156:159], v[48:51]
	v_mfma_f32_16x16x32_bf16 v[40:43], v[140:143], v[156:159], v[40:43]
	v_mfma_f32_16x16x32_bf16 v[32:35], v[132:135], v[164:167], v[32:35]
	v_mfma_f32_16x16x32_bf16 v[24:27], v[140:143], v[164:167], v[24:27]
	s_waitcnt lgkmcnt(0)
	v_mfma_f32_16x16x32_bf16 v[16:19], v[132:135], v[172:175], v[16:19]
	v_mfma_f32_16x16x32_bf16 v[8:11], v[140:143], v[172:175], v[8:11]
	s_barrier
	s_add_u32 s8, s54, 0x24000
	s_addc_u32 s9, s55, 0
	s_mov_b32 m0, s73
	s_nop 0
	global_load_lds_dwordx4 v221, s[8:9]
	s_add_u32 s8, s54, 0x26000
	s_addc_u32 s9, s55, 0
	s_mov_b32 m0, s85
	s_nop 0
	global_load_lds_dwordx4 v221, s[8:9]
	s_waitcnt vmcnt(10)
	s_barrier
	v_mfma_f32_16x16x32_bf16 v[52:55], v[176:179], v[144:147], v[52:55]
	v_mfma_f32_16x16x32_bf16 v[44:47], v[184:187], v[144:147], v[44:47]
	v_mfma_f32_16x16x32_bf16 v[36:39], v[176:179], v[152:155], v[36:39]
	v_mfma_f32_16x16x32_bf16 v[28:31], v[184:187], v[152:155], v[28:31]
	v_mfma_f32_16x16x32_bf16 v[20:23], v[176:179], v[160:163], v[20:23]
	v_mfma_f32_16x16x32_bf16 v[12:15], v[184:187], v[160:163], v[12:15]
	v_mfma_f32_16x16x32_bf16 v[4:7], v[176:179], v[168:171], v[4:7]
	v_mfma_f32_16x16x32_bf16 v[0:3], v[184:187], v[168:171], v[0:3]
	v_mfma_f32_16x16x32_bf16 v[52:55], v[180:183], v[148:151], v[52:55]
	v_mfma_f32_16x16x32_bf16 v[44:47], v[188:191], v[148:151], v[44:47]
	v_mfma_f32_16x16x32_bf16 v[36:39], v[180:183], v[156:159], v[36:39]
	v_mfma_f32_16x16x32_bf16 v[28:31], v[188:191], v[156:159], v[28:31]
	v_mfma_f32_16x16x32_bf16 v[20:23], v[180:183], v[164:167], v[20:23]
	v_mfma_f32_16x16x32_bf16 v[12:15], v[188:191], v[164:167], v[12:15]
	v_mfma_f32_16x16x32_bf16 v[4:7], v[180:183], v[172:175], v[4:7]
	v_mfma_f32_16x16x32_bf16 v[0:3], v[188:191], v[172:175], v[0:3]
	s_add_i32 s95, s95, 2
	s_add_u32 s93, s93, 0x8000
	s_addc_u32 s94, s94, 0
	s_cmp_gt_u32 s95, 5
	s_mov_b64 s[8:9], s[52:53]
	s_barrier

; #define PG8_STAGE(bufoff, gbase, hoff, imm) do { _Pragma("unroll") for (int _i = 0; _i < 2; ++_i) { \
;         asm volatile("s_mov_b32 m0, %0\n\ts_nop 0\n\tglobal_load_lds_dwordx4 %1, %2" \
;             :: "s"(lds0 + (unsigned)((bufoff) + _i * 8192)), "v"(voff0), "s"((const char*)(gbase) + (size_t)(hoff) + (size_t)(_i * 8192)) : "memory"); } } while (0)
; #define PG8_LDA(dst, b, h) do { _Pragma("unroll") for (int m = 0; m < 4; ++m) _Pragma("unroll") for (int k = 0; k < 2; ++k) dst[m][k] = *(const LAS bf16x8*)(lds + PG8_SA(b, h) + aoff + m * 2048 + k * 1024); } while (0)
; #define PG8_LDB(dst, b, h) do { _Pragma("unroll") for (int n = 0; n < 2; ++n) _Pragma("unroll") for (int k = 0; k < 2; ++k) dst[n][k] = *(const LAS bf16x8*)(lds + PG8_SB(b, h) + boff + n * 2048 + k * 1024); } while (0)
; #define PG8_WAIT_V(n) asm volatile("s_waitcnt vmcnt(" #n ")" ::: "memory")
; #define PG8_WAIT_L(n) asm volatile("s_waitcnt lgkmcnt(" #n ")" ::: "memory")
; #define PG8_BAR __builtin_amdgcn_s_barrier()
; template <class Epi>
; __device__ __forceinline__ void gemm_phase(LAS unsigned char* lds, const Gemm g, const StaticOrder& S, const Epi& E) {
;     ...
;         const bool has_next = S.next(ui + 1, nxt);
;         const char* nA = has_next ? (const char*)g.A + (size_t)nxt.pm * tstepA + (size_t)(nxt.pn >> g.gshift) * g.gstride : cA;
;         const char* nB = has_next ? (const char*)g.Bt + (size_t)nxt.pn * tstepB : cB;
;         for (int t = 0; t < nt; t += 2) {
;             const bool last = (t == nt - 2);
;             if (last) E.pre(cur, wid, lane, (unsigned)(size_t)(lds + STAGE_BYTES));
;             const char* aT = cA + (size_t)t * KS;
;             const char* a2 = last ? nA : aT + 2 * KS; const char* b2 = last ? nB : cB + (size_t)(t + 2) * KS;
;             PG8_LDB(B0, 0, 0); PG8_SCHED; PG8_LDA(At, 0, 0); PG8_STAGE(PG8_SA(1, 1), aT + KS, hA, 0);
;             PG8_WAIT_L(8); PG8_BAR; PG8_WAIT_L(0); PG8_MMA(0, 0, At, B0); PG8_BAR; PG8_SCHED;
;             PG8_LDB(B1, 0, 1); PG8_STAGE(PG8_SB(0, 0), b2, 0, 0);
;             PG8_BAR; PG8_WAIT_L(0); PG8_MMA(0, 1, At, B1); PG8_BAR;
;             PG8_LDA(At, 0, 1); PG8_STAGE(PG8_SA(0, 0), a2, 0, 0);
;             PG8_BAR; PG8_WAIT_L(0); PG8_MMA(1, 0, At, B0); PG8_BAR; PG8_SCHED;
;             PG8_STAGE(PG8_SB(0, 1), b2, hB, 0);
;             PG8_WAIT_V(6); PG8_BAR; PG8_MMA(1, 1, At, B1); PG8_BAR;
.LBB0_433:
	s_ashr_i32 s9, s8, 31
	s_lshl_b64 s[0:1], s[8:9], 20
	v_cmp_lt_i64_e32 vcc, s[10:11], v[192:193]
	s_add_u32 s10, s17, s0
	s_addc_u32 s11, s21, s1
	s_and_b64 s[0:1], vcc, exec
	s_cselect_b32 s0, s11, s55
	s_cselect_b32 s1, s10, s54
	s_ashr_i32 s7, s6, 31
	s_lshl_b64 s[52:53], s[6:7], 20
	s_add_u32 s52, s22, s52
	s_addc_u32 s53, s24, s53
	s_and_b64 s[58:59], vcc, exec
	s_cselect_b32 s7, s53, s57
	s_cselect_b32 s9, s52, s56
	s_add_u32 s63, s56, 0x8000
	s_addc_u32 s64, s57, 0
	s_mov_b32 s65, -2
	s_add_u32 s56, s54, 0x8000
	v_add_u32_e32 v128, 0x10000, v133
	s_addc_u32 s57, s55, 0
	ds_read_b128 v[136:139], v128
	ds_read_b128 v[140:143], v128 offset:1024
	ds_read_b128 v[144:147], v128 offset:2048
	ds_read_b128 v[148:151], v128 offset:3072
	s_add_u32 s58, s54, 0x84000
	s_addc_u32 s59, s55, 0
	s_add_u32 s66, s54, 0x86000
	s_addc_u32 s67, s55, 0
	s_cmp_eq_u32 s65, 28
	s_cselect_b32 s55, s0, s57
	s_cselect_b32 s54, s1, s56
	ds_read_b128 v[152:155], v134
	ds_read_b128 v[156:159], v134 offset:1024
	ds_read_b128 v[160:163], v134 offset:2048
	ds_read_b128 v[164:167], v134 offset:3072
	ds_read_b128 v[168:171], v134 offset:4096
	ds_read_b128 v[172:175], v134 offset:5120
	ds_read_b128 v[176:179], v134 offset:6144
	ds_read_b128 v[180:183], v134 offset:7168
	s_mov_b32 m0, s50
	s_nop 0
	global_load_lds_dwordx4 v130, s[58:59]
	s_mov_b32 m0, s51
	s_nop 0
	global_load_lds_dwordx4 v130, s[66:67]
	s_waitcnt lgkmcnt(8)
	s_waitcnt vmcnt(10)
	s_barrier
	s_waitcnt lgkmcnt(7)
	v_mfma_f32_16x16x32_bf16 v[124:127], v[136:139], v[152:155], 0
	v_mfma_f32_16x16x32_bf16 v[120:123], v[144:147], v[152:155], 0
	s_waitcnt lgkmcnt(5)
	v_mfma_f32_16x16x32_bf16 v[116:119], v[136:139], v[160:163], 0
	v_mfma_f32_16x16x32_bf16 v[108:111], v[144:147], v[160:163], 0
	s_waitcnt lgkmcnt(3)
	v_mfma_f32_16x16x32_bf16 v[100:103], v[136:139], v[168:171], 0
	v_mfma_f32_16x16x32_bf16 v[92:95], v[144:147], v[168:171], 0
	s_waitcnt lgkmcnt(1)
	v_mfma_f32_16x16x32_bf16 v[84:87], v[136:139], v[176:179], 0
	v_mfma_f32_16x16x32_bf16 v[76:79], v[144:147], v[176:179], 0
	v_mfma_f32_16x16x32_bf16 v[124:127], v[140:143], v[156:159], v[124:127]
	v_mfma_f32_16x16x32_bf16 v[120:123], v[148:151], v[156:159], v[120:123]
	v_mfma_f32_16x16x32_bf16 v[116:119], v[140:143], v[164:167], v[116:119]
	v_mfma_f32_16x16x32_bf16 v[108:111], v[148:151], v[164:167], v[108:111]
	v_mfma_f32_16x16x32_bf16 v[100:103], v[140:143], v[172:175], v[100:103]
	v_mfma_f32_16x16x32_bf16 v[92:95], v[148:151], v[172:175], v[92:95]
	s_waitcnt lgkmcnt(0)
	v_mfma_f32_16x16x32_bf16 v[84:87], v[140:143], v[180:183], v[84:87]
	v_mfma_f32_16x16x32_bf16 v[76:79], v[148:151], v[180:183], v[76:79]
	s_barrier
	v_add_u32_e32 v128, 0x14000, v133
	ds_read_b128 v[184:187], v128
	ds_read_b128 v[200:203], v128 offset:1024
	ds_read_b128 v[204:207], v128 offset:2048
	ds_read_b128 v[208:211], v128 offset:3072
	s_cselect_b32 s58, s9, s63
	s_cselect_b32 s59, s7, s64
	s_mov_b32 m0, s26
	s_nop 0
	global_load_lds_dwordx4 v130, s[58:59]
	s_add_u32 s66, s58, 0x2000
	s_addc_u32 s67, s59, 0
	s_mov_b32 m0, s27
	s_nop 0
	global_load_lds_dwordx4 v130, s[66:67]
	s_waitcnt vmcnt(10)
	s_barrier
	s_waitcnt lgkmcnt(3)
	v_mfma_f32_16x16x32_bf16 v[112:115], v[184:187], v[152:155], 0
	s_waitcnt lgkmcnt(1)
	v_mfma_f32_16x16x32_bf16 v[104:107], v[204:207], v[152:155], 0
	v_mfma_f32_16x16x32_bf16 v[96:99], v[184:187], v[160:163], 0
	v_mfma_f32_16x16x32_bf16 v[88:91], v[204:207], v[160:163], 0
	v_mfma_f32_16x16x32_bf16 v[80:83], v[184:187], v[168:171], 0
	v_mfma_f32_16x16x32_bf16 v[72:75], v[204:207], v[168:171], 0
	v_mfma_f32_16x16x32_bf16 v[68:71], v[184:187], v[176:179], 0
	v_mfma_f32_16x16x32_bf16 v[64:67], v[204:207], v[176:179], 0
	v_mfma_f32_16x16x32_bf16 v[112:115], v[200:203], v[156:159], v[112:115]
	s_waitcnt lgkmcnt(0)
	v_mfma_f32_16x16x32_bf16 v[104:107], v[208:211], v[156:159], v[104:107]
	v_mfma_f32_16x16x32_bf16 v[96:99], v[200:203], v[164:167], v[96:99]
	v_mfma_f32_16x16x32_bf16 v[88:91], v[208:211], v[164:167], v[88:91]
	v_mfma_f32_16x16x32_bf16 v[80:83], v[200:203], v[172:175], v[80:83]
	v_mfma_f32_16x16x32_bf16 v[72:75], v[208:211], v[172:175], v[72:75]
	v_mfma_f32_16x16x32_bf16 v[68:71], v[200:203], v[180:183], v[68:71]
	v_mfma_f32_16x16x32_bf16 v[64:67], v[208:211], v[180:183], v[64:67]
	s_barrier
	ds_read_b128 v[152:155], v134 offset:16384
	ds_read_b128 v[156:159], v134 offset:17408
	ds_read_b128 v[160:163], v134 offset:18432
	ds_read_b128 v[164:167], v134 offset:19456
	ds_read_b128 v[168:171], v134 offset:20480
	ds_read_b128 v[172:175], v134 offset:21504
	ds_read_b128 v[176:179], v134 offset:22528
	ds_read_b128 v[180:183], v134 offset:23552
	s_mov_b32 m0, s25
	s_nop 0
	global_load_lds_dwordx4 v130, s[54:55]
	s_add_u32 s66, s54, 0x2000
	s_addc_u32 s67, s55, 0
	s_mov_b32 m0, s28
	s_nop 0
	global_load_lds_dwordx4 v130, s[66:67]
	s_barrier
	s_waitcnt lgkmcnt(7)
	v_mfma_f32_16x16x32_bf16 v[60:63], v[136:139], v[152:155], 0
	v_mfma_f32_16x16x32_bf16 v[56:59], v[144:147], v[152:155], 0
	s_waitcnt lgkmcnt(5)
	v_mfma_f32_16x16x32_bf16 v[52:55], v[136:139], v[160:163], 0
	v_mfma_f32_16x16x32_bf16 v[44:47], v[144:147], v[160:163], 0
	s_waitcnt lgkmcnt(3)
	v_mfma_f32_16x16x32_bf16 v[36:39], v[136:139], v[168:171], 0
	v_mfma_f32_16x16x32_bf16 v[28:31], v[144:147], v[168:171], 0
	s_waitcnt lgkmcnt(1)
	v_mfma_f32_16x16x32_bf16 v[20:23], v[136:139], v[176:179], 0
	v_mfma_f32_16x16x32_bf16 v[12:15], v[144:147], v[176:179], 0
	v_mfma_f32_16x16x32_bf16 v[60:63], v[140:143], v[156:159], v[60:63]
	v_mfma_f32_16x16x32_bf16 v[56:59], v[148:151], v[156:159], v[56:59]
	v_mfma_f32_16x16x32_bf16 v[52:55], v[140:143], v[164:167], v[52:55]
	v_mfma_f32_16x16x32_bf16 v[44:47], v[148:151], v[164:167], v[44:47]
	v_mfma_f32_16x16x32_bf16 v[36:39], v[140:143], v[172:175], v[36:39]
	v_mfma_f32_16x16x32_bf16 v[28:31], v[148:151], v[172:175], v[28:31]
	s_waitcnt lgkmcnt(0)
	v_mfma_f32_16x16x32_bf16 v[20:23], v[140:143], v[180:183], v[20:23]
	v_mfma_f32_16x16x32_bf16 v[12:15], v[148:151], v[180:183], v[12:15]
	s_barrier
; #define PG8_STAGE(bufoff, gbase, hoff, imm) do { _Pragma("unroll") for (int _i = 0; _i < 2; ++_i) { \
;         asm volatile("s_mov_b32 m0, %0\n\ts_nop 0\n\tglobal_load_lds_dwordx4 %1, %2" \
;             :: "s"(lds0 + (unsigned)((bufoff) + _i * 8192)), "v"(voff0), "s"((const char*)(gbase) + (size_t)(hoff) + (size_t)(_i * 8192)) : "memory"); } } while (0)
; #define PG8_LDA(dst, b, h) do { _Pragma("unroll") for (int m = 0; m < 4; ++m) _Pragma("unroll") for (int k = 0; k < 2; ++k) dst[m][k] = *(const LAS bf16x8*)(lds + PG8_SA(b, h) + aoff + m * 2048 + k * 1024); } while (0)
; #define PG8_LDB(dst, b, h) do { _Pragma("unroll") for (int n = 0; n < 2; ++n) _Pragma("unroll") for (int k = 0; k < 2; ++k) dst[n][k] = *(const LAS bf16x8*)(lds + PG8_SB(b, h) + boff + n * 2048 + k * 1024); } while (0)
; #define PG8_MMA(ai, bj, At, Bt) do { __builtin_amdgcn_s_setprio(1); _Pragma("unroll") for (int m = 0; m < 4; ++m) _Pragma("unroll") for (int n = 0; n < 2; ++n) _Pragma("unroll") for (int k = 0; k < 2; ++k) \
;         acc[ai][bj][m][n] = __builtin_amdgcn_mfma_f32_16x16x32_bf16(Bt[n][k], At[m][k], acc[ai][bj][m][n], 0, 0, 0); __builtin_amdgcn_s_setprio(0); } while (0)
; #define PG8_WAIT_V(n) asm volatile("s_waitcnt vmcnt(" #n ")" ::: "memory")
; #define PG8_WAIT_L(n) asm volatile("s_waitcnt lgkmcnt(" #n ")" ::: "memory")
; #define PG8_BAR __builtin_amdgcn_s_barrier()
; #define PG8_SCHED __builtin_amdgcn_sched_barrier(0)
; template <class Epi>
; __device__ __forceinline__ void gemm_phase(LAS unsigned char* lds, const Gemm g, const StaticOrder& S, const Epi& E) {
;     ...
;             PG8_STAGE(PG8_SB(0, 1), b2, hB, 0);
;             PG8_WAIT_V(6); PG8_BAR; PG8_MMA(1, 1, At, B1); PG8_BAR;
;             PG8_LDB(B0, 1, 0); PG8_SCHED; PG8_LDA(At, 1, 0); PG8_STAGE(PG8_SA(0, 1), a2, hA, 0);
;             PG8_WAIT_L(8); PG8_BAR; PG8_WAIT_L(0); PG8_MMA(0, 0, At, B0); PG8_BAR; PG8_SCHED;
;             PG8_LDB(B1, 1, 1); PG8_STAGE(PG8_SB(1, 0), b2 + KS, 0, 0);
;             PG8_BAR; PG8_WAIT_L(0); PG8_MMA(0, 1, At, B1); PG8_BAR;
;             PG8_LDA(At, 1, 1); PG8_STAGE(PG8_SA(1, 0), a2 + KS, 0, 0);
	s_add_u32 s66, s58, 0x80000
	s_addc_u32 s67, s59, 0
	s_mov_b32 m0, s29
	s_nop 0
	global_load_lds_dwordx4 v130, s[66:67]
	s_add_u32 s66, s58, 0x82000
	s_addc_u32 s67, s59, 0
	s_mov_b32 m0, s30
	s_nop 0
	global_load_lds_dwordx4 v130, s[66:67]
	s_waitcnt vmcnt(10)
	s_barrier
	v_mfma_f32_16x16x32_bf16 v[48:51], v[184:187], v[152:155], 0
	v_mfma_f32_16x16x32_bf16 v[40:43], v[204:207], v[152:155], 0
	v_mfma_f32_16x16x32_bf16 v[32:35], v[184:187], v[160:163], 0
	v_mfma_f32_16x16x32_bf16 v[24:27], v[204:207], v[160:163], 0
	v_mfma_f32_16x16x32_bf16 v[16:19], v[184:187], v[168:171], 0
	v_mfma_f32_16x16x32_bf16 v[8:11], v[204:207], v[168:171], 0
	v_mfma_f32_16x16x32_bf16 v[4:7], v[184:187], v[176:179], 0
	v_mfma_f32_16x16x32_bf16 v[0:3], v[204:207], v[176:179], 0
	v_mfma_f32_16x16x32_bf16 v[48:51], v[200:203], v[156:159], v[48:51]
	v_mfma_f32_16x16x32_bf16 v[40:43], v[208:211], v[156:159], v[40:43]
	v_mfma_f32_16x16x32_bf16 v[32:35], v[200:203], v[164:167], v[32:35]
	v_mfma_f32_16x16x32_bf16 v[24:27], v[208:211], v[164:167], v[24:27]
	v_mfma_f32_16x16x32_bf16 v[16:19], v[200:203], v[172:175], v[16:19]
	v_mfma_f32_16x16x32_bf16 v[8:11], v[208:211], v[172:175], v[8:11]
	v_mfma_f32_16x16x32_bf16 v[4:7], v[200:203], v[180:183], v[4:7]
	v_mfma_f32_16x16x32_bf16 v[0:3], v[208:211], v[180:183], v[0:3]
	v_add_u32_e32 v128, 0x18000, v133
	s_barrier
	ds_read_b128 v[136:139], v128
	ds_read_b128 v[140:143], v128 offset:1024
	ds_read_b128 v[144:147], v128 offset:2048
	ds_read_b128 v[148:151], v128 offset:3072
	ds_read_b128 v[152:155], v134 offset:32768
	ds_read_b128 v[156:159], v134 offset:33792
	ds_read_b128 v[160:163], v134 offset:34816
	ds_read_b128 v[164:167], v134 offset:35840
	ds_read_b128 v[168:171], v134 offset:36864
	ds_read_b128 v[172:175], v134 offset:37888
	ds_read_b128 v[176:179], v134 offset:38912
	ds_read_b128 v[180:183], v134 offset:39936
	s_add_u32 s66, s54, 0x80000
	s_addc_u32 s67, s55, 0
	s_mov_b32 m0, s34
	s_nop 0
	global_load_lds_dwordx4 v130, s[66:67]
	s_add_u32 s66, s54, 0x82000
	s_addc_u32 s67, s55, 0
	s_mov_b32 m0, s37
	s_nop 0
	global_load_lds_dwordx4 v130, s[66:67]
	s_waitcnt lgkmcnt(8)
	s_waitcnt vmcnt(10)
	s_barrier
	s_waitcnt lgkmcnt(7)
	v_mfma_f32_16x16x32_bf16 v[124:127], v[136:139], v[152:155], v[124:127]
	v_mfma_f32_16x16x32_bf16 v[120:123], v[144:147], v[152:155], v[120:123]
	s_waitcnt lgkmcnt(5)
	v_mfma_f32_16x16x32_bf16 v[116:119], v[136:139], v[160:163], v[116:119]
	v_mfma_f32_16x16x32_bf16 v[108:111], v[144:147], v[160:163], v[108:111]
	s_waitcnt lgkmcnt(3)
	v_mfma_f32_16x16x32_bf16 v[100:103], v[136:139], v[168:171], v[100:103]
	v_mfma_f32_16x16x32_bf16 v[92:95], v[144:147], v[168:171], v[92:95]
	s_waitcnt lgkmcnt(1)
	v_mfma_f32_16x16x32_bf16 v[84:87], v[136:139], v[176:179], v[84:87]
	v_mfma_f32_16x16x32_bf16 v[76:79], v[144:147], v[176:179], v[76:79]
	v_mfma_f32_16x16x32_bf16 v[124:127], v[140:143], v[156:159], v[124:127]
	v_mfma_f32_16x16x32_bf16 v[120:123], v[148:151], v[156:159], v[120:123]
	v_mfma_f32_16x16x32_bf16 v[116:119], v[140:143], v[164:167], v[116:119]
	v_mfma_f32_16x16x32_bf16 v[108:111], v[148:151], v[164:167], v[108:111]
	v_mfma_f32_16x16x32_bf16 v[100:103], v[140:143], v[172:175], v[100:103]
	v_mfma_f32_16x16x32_bf16 v[92:95], v[148:151], v[172:175], v[92:95]
	s_waitcnt lgkmcnt(0)
	v_mfma_f32_16x16x32_bf16 v[84:87], v[140:143], v[180:183], v[84:87]
	v_mfma_f32_16x16x32_bf16 v[76:79], v[148:151], v[180:183], v[76:79]
	s_barrier
	v_add_u32_e32 v128, 0x1c000, v133
	ds_read_b128 v[184:187], v128
	ds_read_b128 v[200:203], v128 offset:1024
	ds_read_b128 v[204:207], v128 offset:2048
	ds_read_b128 v[208:211], v128 offset:3072
	s_add_u32 s66, s58, 0x4000
	s_addc_u32 s67, s59, 0
	s_mov_b32 m0, s38
	s_nop 0
	global_load_lds_dwordx4 v130, s[66:67]
	s_add_u32 s66, s58, 0x6000
	s_addc_u32 s67, s59, 0
	s_mov_b32 m0, s39
	s_nop 0
	global_load_lds_dwordx4 v130, s[66:67]
	s_waitcnt vmcnt(10)
	s_barrier
; #define PG8_STAGE(bufoff, gbase, hoff, imm) do { _Pragma("unroll") for (int _i = 0; _i < 2; ++_i) { \
;         asm volatile("s_mov_b32 m0, %0\n\ts_nop 0\n\tglobal_load_lds_dwordx4 %1, %2" \
;             :: "s"(lds0 + (unsigned)((bufoff) + _i * 8192)), "v"(voff0), "s"((const char*)(gbase) + (size_t)(hoff) + (size_t)(_i * 8192)) : "memory"); } } while (0)
; #define PG8_LDA(dst, b, h) do { _Pragma("unroll") for (int m = 0; m < 4; ++m) _Pragma("unroll") for (int k = 0; k < 2; ++k) dst[m][k] = *(const LAS bf16x8*)(lds + PG8_SA(b, h) + aoff + m * 2048 + k * 1024); } while (0)
; #define PG8_MMA(ai, bj, At, Bt) do { __builtin_amdgcn_s_setprio(1); _Pragma("unroll") for (int m = 0; m < 4; ++m) _Pragma("unroll") for (int n = 0; n < 2; ++n) _Pragma("unroll") for (int k = 0; k < 2; ++k) \
;         acc[ai][bj][m][n] = __builtin_amdgcn_mfma_f32_16x16x32_bf16(Bt[n][k], At[m][k], acc[ai][bj][m][n], 0, 0, 0); __builtin_amdgcn_s_setprio(0); } while (0)
; #define PG8_WAIT_V(n) asm volatile("s_waitcnt vmcnt(" #n ")" ::: "memory")
; #define PG8_WAIT_L(n) asm volatile("s_waitcnt lgkmcnt(" #n ")" ::: "memory")
; #define PG8_BAR __builtin_amdgcn_s_barrier()
; #define PG8_SCHED __builtin_amdgcn_sched_barrier(0)
; template <class Epi>
; __device__ __forceinline__ void gemm_phase(LAS unsigned char* lds, const Gemm g, const StaticOrder& S, const Epi& E) {
;     ...
;             PG8_LDA(At, 1, 1); PG8_STAGE(PG8_SA(1, 0), a2 + KS, 0, 0);
;             PG8_BAR; PG8_WAIT_L(0); PG8_MMA(1, 0, At, B0); PG8_BAR; PG8_SCHED;
;             PG8_STAGE(PG8_SB(1, 1), b2 + KS, hB, 0);
;             PG8_WAIT_V(6); PG8_BAR; PG8_MMA(1, 1, At, B1); PG8_BAR;
	s_waitcnt lgkmcnt(3)
	v_mfma_f32_16x16x32_bf16 v[112:115], v[184:187], v[152:155], v[112:115]
	s_waitcnt lgkmcnt(1)
	v_mfma_f32_16x16x32_bf16 v[104:107], v[204:207], v[152:155], v[104:107]
	v_mfma_f32_16x16x32_bf16 v[96:99], v[184:187], v[160:163], v[96:99]
	v_mfma_f32_16x16x32_bf16 v[88:91], v[204:207], v[160:163], v[88:91]
	v_mfma_f32_16x16x32_bf16 v[80:83], v[184:187], v[168:171], v[80:83]
	v_mfma_f32_16x16x32_bf16 v[72:75], v[204:207], v[168:171], v[72:75]
	v_mfma_f32_16x16x32_bf16 v[68:71], v[184:187], v[176:179], v[68:71]
	v_mfma_f32_16x16x32_bf16 v[64:67], v[204:207], v[176:179], v[64:67]
	v_mfma_f32_16x16x32_bf16 v[112:115], v[200:203], v[156:159], v[112:115]
	s_waitcnt lgkmcnt(0)
	v_mfma_f32_16x16x32_bf16 v[104:107], v[208:211], v[156:159], v[104:107]
	v_mfma_f32_16x16x32_bf16 v[96:99], v[200:203], v[164:167], v[96:99]
	v_mfma_f32_16x16x32_bf16 v[88:91], v[208:211], v[164:167], v[88:91]
	v_mfma_f32_16x16x32_bf16 v[80:83], v[200:203], v[172:175], v[80:83]
	v_mfma_f32_16x16x32_bf16 v[72:75], v[208:211], v[172:175], v[72:75]
	v_mfma_f32_16x16x32_bf16 v[68:71], v[200:203], v[180:183], v[68:71]
	v_mfma_f32_16x16x32_bf16 v[64:67], v[208:211], v[180:183], v[64:67]
	s_barrier
	ds_read_b128 v[152:155], v134 offset:49152
	ds_read_b128 v[156:159], v134 offset:50176
	ds_read_b128 v[160:163], v134 offset:51200
	ds_read_b128 v[164:167], v134 offset:52224
	ds_read_b128 v[168:171], v134 offset:53248
	ds_read_b128 v[172:175], v134 offset:54272
	ds_read_b128 v[176:179], v134 offset:55296
	ds_read_b128 v[180:183], v134 offset:56320
	s_add_u32 s66, s54, 0x4000
	s_addc_u32 s67, s55, 0
	s_mov_b32 m0, s40
	s_nop 0
	global_load_lds_dwordx4 v130, s[66:67]
	s_add_u32 s54, s54, 0x6000
	s_addc_u32 s55, s55, 0
	s_mov_b32 m0, s41
	s_nop 0
	global_load_lds_dwordx4 v130, s[54:55]
	s_barrier
	s_waitcnt lgkmcnt(7)
	v_mfma_f32_16x16x32_bf16 v[60:63], v[136:139], v[152:155], v[60:63]
	v_mfma_f32_16x16x32_bf16 v[56:59], v[144:147], v[152:155], v[56:59]
	s_waitcnt lgkmcnt(5)
	v_mfma_f32_16x16x32_bf16 v[52:55], v[136:139], v[160:163], v[52:55]
	v_mfma_f32_16x16x32_bf16 v[44:47], v[144:147], v[160:163], v[44:47]
	s_waitcnt lgkmcnt(3)
	v_mfma_f32_16x16x32_bf16 v[36:39], v[136:139], v[168:171], v[36:39]
	v_mfma_f32_16x16x32_bf16 v[28:31], v[144:147], v[168:171], v[28:31]
	s_waitcnt lgkmcnt(1)
	v_mfma_f32_16x16x32_bf16 v[20:23], v[136:139], v[176:179], v[20:23]
	v_mfma_f32_16x16x32_bf16 v[12:15], v[144:147], v[176:179], v[12:15]
	v_mfma_f32_16x16x32_bf16 v[60:63], v[140:143], v[156:159], v[60:63]
	v_mfma_f32_16x16x32_bf16 v[56:59], v[148:151], v[156:159], v[56:59]
	v_mfma_f32_16x16x32_bf16 v[52:55], v[140:143], v[164:167], v[52:55]
	v_mfma_f32_16x16x32_bf16 v[44:47], v[148:151], v[164:167], v[44:47]
	v_mfma_f32_16x16x32_bf16 v[36:39], v[140:143], v[172:175], v[36:39]
	v_mfma_f32_16x16x32_bf16 v[28:31], v[148:151], v[172:175], v[28:31]
	s_waitcnt lgkmcnt(0)
	v_mfma_f32_16x16x32_bf16 v[20:23], v[140:143], v[180:183], v[20:23]
	v_mfma_f32_16x16x32_bf16 v[12:15], v[148:151], v[180:183], v[12:15]
	s_barrier
	s_add_u32 s54, s58, 0x84000
	s_addc_u32 s55, s59, 0
	s_mov_b32 m0, s42
	s_nop 0
	global_load_lds_dwordx4 v130, s[54:55]
	s_add_u32 s54, s58, 0x86000
	s_addc_u32 s55, s59, 0
	s_mov_b32 m0, s43
	s_nop 0
	global_load_lds_dwordx4 v130, s[54:55]
	s_waitcnt vmcnt(10)
	s_barrier
	v_mfma_f32_16x16x32_bf16 v[48:51], v[184:187], v[152:155], v[48:51]
	v_mfma_f32_16x16x32_bf16 v[40:43], v[204:207], v[152:155], v[40:43]
	v_mfma_f32_16x16x32_bf16 v[32:35], v[184:187], v[160:163], v[32:35]
	v_mfma_f32_16x16x32_bf16 v[24:27], v[204:207], v[160:163], v[24:27]
	v_mfma_f32_16x16x32_bf16 v[16:19], v[184:187], v[168:171], v[16:19]
	v_mfma_f32_16x16x32_bf16 v[8:11], v[204:207], v[168:171], v[8:11]
	v_mfma_f32_16x16x32_bf16 v[4:7], v[184:187], v[176:179], v[4:7]
	v_mfma_f32_16x16x32_bf16 v[0:3], v[204:207], v[176:179], v[0:3]
	v_mfma_f32_16x16x32_bf16 v[48:51], v[200:203], v[156:159], v[48:51]
	v_mfma_f32_16x16x32_bf16 v[40:43], v[208:211], v[156:159], v[40:43]
	v_mfma_f32_16x16x32_bf16 v[32:35], v[200:203], v[164:167], v[32:35]
	v_mfma_f32_16x16x32_bf16 v[24:27], v[208:211], v[164:167], v[24:27]
	v_mfma_f32_16x16x32_bf16 v[16:19], v[200:203], v[172:175], v[16:19]
	v_mfma_f32_16x16x32_bf16 v[8:11], v[208:211], v[172:175], v[8:11]
	v_mfma_f32_16x16x32_bf16 v[4:7], v[200:203], v[180:183], v[4:7]
	v_mfma_f32_16x16x32_bf16 v[0:3], v[208:211], v[180:183], v[0:3]
	s_add_i32 s65, s65, 2
	s_add_u32 s63, s63, 0x8000
	s_addc_u32 s64, s64, 0
	s_cmp_gt_u32 s65, 29
	s_mov_b64 s[54:55], s[56:57]
	s_barrier

; #define PG8_STAGE(bufoff, gbase, hoff, imm) do { _Pragma("unroll") for (int _i = 0; _i < 2; ++_i) { \
;         asm volatile("s_mov_b32 m0, %0\n\ts_nop 0\n\tglobal_load_lds_dwordx4 %1, %2" \
;             :: "s"(lds0 + (unsigned)((bufoff) + _i * 8192)), "v"(voff0), "s"((const char*)(gbase) + (size_t)(hoff) + (size_t)(_i * 8192)) : "memory"); } } while (0)
; #define PG8_LDA(dst, b, h) do { _Pragma("unroll") for (int m = 0; m < 4; ++m) _Pragma("unroll") for (int k = 0; k < 2; ++k) dst[m][k] = *(const LAS bf16x8*)(lds + PG8_SA(b, h) + aoff + m * 2048 + k * 1024); } while (0)
; #define PG8_LDB(dst, b, h) do { _Pragma("unroll") for (int n = 0; n < 2; ++n) _Pragma("unroll") for (int k = 0; k < 2; ++k) dst[n][k] = *(const LAS bf16x8*)(lds + PG8_SB(b, h) + boff + n * 2048 + k * 1024); } while (0)
; #define PG8_WAIT_V(n) asm volatile("s_waitcnt vmcnt(" #n ")" ::: "memory")
; #define PG8_WAIT_L(n) asm volatile("s_waitcnt lgkmcnt(" #n ")" ::: "memory")
; #define PG8_BAR __builtin_amdgcn_s_barrier()
; template <class Epi>
; __device__ __forceinline__ void gemm_phase(LAS unsigned char* lds, const Gemm g, const StaticOrder& S, const Epi& E) {
;     ...
;         const bool has_next = S.next(ui + 1, nxt);
;         const char* nA = has_next ? (const char*)g.A + (size_t)nxt.pm * tstepA + (size_t)(nxt.pn >> g.gshift) * g.gstride : cA;
;         const char* nB = has_next ? (const char*)g.Bt + (size_t)nxt.pn * tstepB : cB;
;         for (int t = 0; t < nt; t += 2) {
;             const bool last = (t == nt - 2);
;             if (last) E.pre(cur, wid, lane, (unsigned)(size_t)(lds + STAGE_BYTES));
;             const char* aT = cA + (size_t)t * KS;
;             const char* a2 = last ? nA : aT + 2 * KS; const char* b2 = last ? nB : cB + (size_t)(t + 2) * KS;
;             PG8_LDB(B0, 0, 0); PG8_SCHED; PG8_LDA(At, 0, 0); PG8_STAGE(PG8_SA(1, 1), aT + KS, hA, 0);
;             PG8_WAIT_L(8); PG8_BAR; PG8_WAIT_L(0); PG8_MMA(0, 0, At, B0); PG8_BAR; PG8_SCHED;
;             PG8_LDB(B1, 0, 1); PG8_STAGE(PG8_SB(0, 0), b2, 0, 0);
;             PG8_BAR; PG8_WAIT_L(0); PG8_MMA(0, 1, At, B1); PG8_BAR;
;             PG8_LDA(At, 0, 1); PG8_STAGE(PG8_SA(0, 0), a2, 0, 0);
;             PG8_BAR; PG8_WAIT_L(0); PG8_MMA(1, 0, At, B0); PG8_BAR; PG8_SCHED;
;             PG8_STAGE(PG8_SB(0, 1), b2, hB, 0);
;             PG8_WAIT_V(6); PG8_BAR; PG8_MMA(1, 1, At, B1); PG8_BAR;
.LBB0_505:
	s_ashr_i32 s71, s70, 31
	v_cmp_lt_i64_e32 vcc, s[8:9], v[194:195]
	s_lshl_b64 s[8:9], s[70:71], 20
	s_add_u32 s72, s16, s8
	s_addc_u32 s73, s17, s9
	s_and_b64 s[8:9], vcc, exec
	s_cselect_b32 s51, s73, s79
	s_cselect_b32 s71, s72, s78
	s_ashr_i32 s69, s68, 31
	s_lshl_b64 s[8:9], s[68:69], 20
	s_add_u32 s74, s21, s8
	s_addc_u32 s75, s22, s9
	s_and_b64 s[8:9], vcc, exec
	s_cselect_b32 s69, s75, s81
	s_cselect_b32 s62, s74, s80
	s_lshl_b32 s8, s0, 7
	s_ashr_i32 s9, s8, 31
	s_lshl_b64 s[0:1], s[8:9], 2
	s_add_u32 s76, s12, s0
	s_addc_u32 s77, s97, s1
	s_add_u32 s9, s80, 0x8000
	s_addc_u32 s63, s81, 0
	s_mov_b32 s0, -2
	s_mov_b64 s[84:85], 0
	v_add_u32_e32 v140, 0x10000, v202
	ds_read_b128 v[128:131], v140
	ds_read_b128 v[132:135], v140 offset:1024
	ds_read_b128 v[136:139], v140 offset:2048
	ds_read_b128 v[140:143], v140 offset:3072
	s_add_u32 s80, s78, 0x8000
	s_addc_u32 s81, s79, 0
	s_and_b64 s[82:83], s[84:85], exec
	s_cselect_b32 s83, s51, s81
	s_cselect_b32 s82, s71, s80
	ds_read_b128 v[144:147], v203
	ds_read_b128 v[148:151], v203 offset:1024
	ds_read_b128 v[152:155], v203 offset:2048
	ds_read_b128 v[156:159], v203 offset:3072
	ds_read_b128 v[160:163], v203 offset:4096
	ds_read_b128 v[164:167], v203 offset:5120
	ds_read_b128 v[204:207], v203 offset:6144
	ds_read_b128 v[208:211], v203 offset:7168
	s_add_u32 s48, s78, 0x84000
	s_addc_u32 s49, s79, 0
	s_mov_b32 m0, s87
	s_nop 0
	global_load_lds_dwordx4 v168, s[48:49]
	s_add_u32 s48, s78, 0x86000
	s_addc_u32 s49, s79, 0
	s_mov_b32 m0, s96
	s_nop 0
	global_load_lds_dwordx4 v168, s[48:49]
	s_waitcnt lgkmcnt(8)
	s_waitcnt vmcnt(10)
	s_barrier
	s_waitcnt lgkmcnt(7)
	v_mfma_f32_16x16x32_bf16 v[96:99], v[128:131], v[144:147], 0
	v_mfma_f32_16x16x32_bf16 v[44:47], v[136:139], v[144:147], 0
	s_waitcnt lgkmcnt(5)
	v_mfma_f32_16x16x32_bf16 v[92:95], v[128:131], v[152:155], 0
	v_mfma_f32_16x16x32_bf16 v[40:43], v[136:139], v[152:155], 0
	s_waitcnt lgkmcnt(3)
	v_mfma_f32_16x16x32_bf16 v[84:87], v[128:131], v[160:163], 0
	v_mfma_f32_16x16x32_bf16 v[36:39], v[136:139], v[160:163], 0
	s_waitcnt lgkmcnt(1)
	v_mfma_f32_16x16x32_bf16 v[124:127], v[128:131], v[204:207], 0
	v_mfma_f32_16x16x32_bf16 v[120:123], v[136:139], v[204:207], 0
	v_mfma_f32_16x16x32_bf16 v[96:99], v[132:135], v[148:151], v[96:99]
	v_mfma_f32_16x16x32_bf16 v[44:47], v[140:143], v[148:151], v[44:47]
	v_mfma_f32_16x16x32_bf16 v[92:95], v[132:135], v[156:159], v[92:95]
	v_mfma_f32_16x16x32_bf16 v[40:43], v[140:143], v[156:159], v[40:43]
	v_mfma_f32_16x16x32_bf16 v[84:87], v[132:135], v[164:167], v[84:87]
	v_mfma_f32_16x16x32_bf16 v[36:39], v[140:143], v[164:167], v[36:39]
	s_waitcnt lgkmcnt(0)
	v_mfma_f32_16x16x32_bf16 v[124:127], v[132:135], v[208:211], v[124:127]
	v_mfma_f32_16x16x32_bf16 v[120:123], v[140:143], v[208:211], v[120:123]
	s_barrier
	v_add_u32_e32 v188, 0x14000, v202
	ds_read_b128 v[212:215], v188
	ds_read_b128 v[236:239], v188 offset:1024
	ds_read_b128 v[240:243], v188 offset:2048
	ds_read_b128 v[244:247], v188 offset:3072
	s_and_b64 s[48:49], s[84:85], exec
	s_cselect_b32 s78, s62, s9
	s_cselect_b32 s79, s69, s63
	s_mov_b32 m0, s25
	s_nop 0
	global_load_lds_dwordx4 v168, s[78:79]
	s_add_u32 s48, s78, 0x2000
	s_addc_u32 s49, s79, 0
	s_mov_b32 m0, s26
	s_nop 0
	global_load_lds_dwordx4 v168, s[48:49]
	s_waitcnt vmcnt(10)
	s_barrier
	s_waitcnt lgkmcnt(3)
	v_mfma_f32_16x16x32_bf16 v[80:83], v[212:215], v[144:147], 0
	s_waitcnt lgkmcnt(1)
	v_mfma_f32_16x16x32_bf16 v[32:35], v[240:243], v[144:147], 0
	v_mfma_f32_16x16x32_bf16 v[76:79], v[212:215], v[152:155], 0
	v_mfma_f32_16x16x32_bf16 v[28:31], v[240:243], v[152:155], 0
	v_mfma_f32_16x16x32_bf16 v[72:75], v[212:215], v[160:163], 0
	v_mfma_f32_16x16x32_bf16 v[24:27], v[240:243], v[160:163], 0
	v_mfma_f32_16x16x32_bf16 v[116:119], v[212:215], v[204:207], 0
	v_mfma_f32_16x16x32_bf16 v[112:115], v[240:243], v[204:207], 0
	v_mfma_f32_16x16x32_bf16 v[80:83], v[236:239], v[148:151], v[80:83]
	s_waitcnt lgkmcnt(0)
	v_mfma_f32_16x16x32_bf16 v[32:35], v[244:247], v[148:151], v[32:35]
	v_mfma_f32_16x16x32_bf16 v[76:79], v[236:239], v[156:159], v[76:79]
	v_mfma_f32_16x16x32_bf16 v[28:31], v[244:247], v[156:159], v[28:31]
	v_mfma_f32_16x16x32_bf16 v[72:75], v[236:239], v[164:167], v[72:75]
	v_mfma_f32_16x16x32_bf16 v[24:27], v[244:247], v[164:167], v[24:27]
	v_mfma_f32_16x16x32_bf16 v[116:119], v[236:239], v[208:211], v[116:119]
	v_mfma_f32_16x16x32_bf16 v[112:115], v[244:247], v[208:211], v[112:115]
	s_barrier
	ds_read_b128 v[144:147], v203 offset:16384
	ds_read_b128 v[148:151], v203 offset:17408
	ds_read_b128 v[152:155], v203 offset:18432
	ds_read_b128 v[156:159], v203 offset:19456
	ds_read_b128 v[160:163], v203 offset:20480
	ds_read_b128 v[164:167], v203 offset:21504
	ds_read_b128 v[204:207], v203 offset:22528
	ds_read_b128 v[208:211], v203 offset:23552
	s_mov_b32 m0, s24
	s_nop 0
	global_load_lds_dwordx4 v168, s[82:83]
	s_add_u32 s48, s82, 0x2000
	s_addc_u32 s49, s83, 0
	s_mov_b32 m0, s27
	s_nop 0
	global_load_lds_dwordx4 v168, s[48:49]
	s_barrier
	s_waitcnt lgkmcnt(7)
	v_mfma_f32_16x16x32_bf16 v[68:71], v[128:131], v[144:147], 0
	v_mfma_f32_16x16x32_bf16 v[20:23], v[136:139], v[144:147], 0
	s_waitcnt lgkmcnt(5)
	v_mfma_f32_16x16x32_bf16 v[64:67], v[128:131], v[152:155], 0
	v_mfma_f32_16x16x32_bf16 v[16:19], v[136:139], v[152:155], 0
	s_waitcnt lgkmcnt(3)
	v_mfma_f32_16x16x32_bf16 v[60:63], v[128:131], v[160:163], 0
	v_mfma_f32_16x16x32_bf16 v[12:15], v[136:139], v[160:163], 0
	s_waitcnt lgkmcnt(1)
	v_mfma_f32_16x16x32_bf16 v[108:111], v[128:131], v[204:207], 0
	v_mfma_f32_16x16x32_bf16 v[104:107], v[136:139], v[204:207], 0
	v_mfma_f32_16x16x32_bf16 v[68:71], v[132:135], v[148:151], v[68:71]
	v_mfma_f32_16x16x32_bf16 v[20:23], v[140:143], v[148:151], v[20:23]
	v_mfma_f32_16x16x32_bf16 v[64:67], v[132:135], v[156:159], v[64:67]
	v_mfma_f32_16x16x32_bf16 v[16:19], v[140:143], v[156:159], v[16:19]
	v_mfma_f32_16x16x32_bf16 v[60:63], v[132:135], v[164:167], v[60:63]
	v_mfma_f32_16x16x32_bf16 v[12:15], v[140:143], v[164:167], v[12:15]
	s_waitcnt lgkmcnt(0)
	v_mfma_f32_16x16x32_bf16 v[108:111], v[132:135], v[208:211], v[108:111]
	v_mfma_f32_16x16x32_bf16 v[104:107], v[140:143], v[208:211], v[104:107]
	s_barrier
; #define PG8_STAGE(bufoff, gbase, hoff, imm) do { _Pragma("unroll") for (int _i = 0; _i < 2; ++_i) { \
;         asm volatile("s_mov_b32 m0, %0\n\ts_nop 0\n\tglobal_load_lds_dwordx4 %1, %2" \
;             :: "s"(lds0 + (unsigned)((bufoff) + _i * 8192)), "v"(voff0), "s"((const char*)(gbase) + (size_t)(hoff) + (size_t)(_i * 8192)) : "memory"); } } while (0)
; #define PG8_LDA(dst, b, h) do { _Pragma("unroll") for (int m = 0; m < 4; ++m) _Pragma("unroll") for (int k = 0; k < 2; ++k) dst[m][k] = *(const LAS bf16x8*)(lds + PG8_SA(b, h) + aoff + m * 2048 + k * 1024); } while (0)
; #define PG8_LDB(dst, b, h) do { _Pragma("unroll") for (int n = 0; n < 2; ++n) _Pragma("unroll") for (int k = 0; k < 2; ++k) dst[n][k] = *(const LAS bf16x8*)(lds + PG8_SB(b, h) + boff + n * 2048 + k * 1024); } while (0)
; #define PG8_MMA(ai, bj, At, Bt) do { __builtin_amdgcn_s_setprio(1); _Pragma("unroll") for (int m = 0; m < 4; ++m) _Pragma("unroll") for (int n = 0; n < 2; ++n) _Pragma("unroll") for (int k = 0; k < 2; ++k) \
;         acc[ai][bj][m][n] = __builtin_amdgcn_mfma_f32_16x16x32_bf16(Bt[n][k], At[m][k], acc[ai][bj][m][n], 0, 0, 0); __builtin_amdgcn_s_setprio(0); } while (0)
; #define PG8_WAIT_V(n) asm volatile("s_waitcnt vmcnt(" #n ")" ::: "memory")
; #define PG8_WAIT_L(n) asm volatile("s_waitcnt lgkmcnt(" #n ")" ::: "memory")
; #define PG8_BAR __builtin_amdgcn_s_barrier()
; #define PG8_SCHED __builtin_amdgcn_sched_barrier(0)
; template <class Epi>
; __device__ __forceinline__ void gemm_phase(LAS unsigned char* lds, const Gemm g, const StaticOrder& S, const Epi& E) {
;     ...
;             PG8_STAGE(PG8_SB(0, 1), b2, hB, 0);
;             PG8_WAIT_V(6); PG8_BAR; PG8_MMA(1, 1, At, B1); PG8_BAR;
;             PG8_LDB(B0, 1, 0); PG8_SCHED; PG8_LDA(At, 1, 0); PG8_STAGE(PG8_SA(0, 1), a2, hA, 0);
;             PG8_WAIT_L(8); PG8_BAR; PG8_WAIT_L(0); PG8_MMA(0, 0, At, B0); PG8_BAR; PG8_SCHED;
;             PG8_LDB(B1, 1, 1); PG8_STAGE(PG8_SB(1, 0), b2 + KS, 0, 0);
;             PG8_BAR; PG8_WAIT_L(0); PG8_MMA(0, 1, At, B1); PG8_BAR;
;             PG8_LDA(At, 1, 1); PG8_STAGE(PG8_SA(1, 0), a2 + KS, 0, 0);
	s_add_u32 s48, s78, 0x80000
	s_addc_u32 s49, s79, 0
	s_mov_b32 m0, s28
	s_nop 0
	global_load_lds_dwordx4 v168, s[48:49]
	s_add_u32 s48, s78, 0x82000
	s_addc_u32 s49, s79, 0
	s_mov_b32 m0, s29
	s_nop 0
	global_load_lds_dwordx4 v168, s[48:49]
	s_waitcnt vmcnt(10)
	s_barrier
	v_mfma_f32_16x16x32_bf16 v[56:59], v[212:215], v[144:147], 0
	v_mfma_f32_16x16x32_bf16 v[8:11], v[240:243], v[144:147], 0
	v_mfma_f32_16x16x32_bf16 v[52:55], v[212:215], v[152:155], 0
	v_mfma_f32_16x16x32_bf16 v[4:7], v[240:243], v[152:155], 0
	v_mfma_f32_16x16x32_bf16 v[48:51], v[212:215], v[160:163], 0
	v_mfma_f32_16x16x32_bf16 v[0:3], v[240:243], v[160:163], 0
	v_mfma_f32_16x16x32_bf16 v[100:103], v[212:215], v[204:207], 0
	v_mfma_f32_16x16x32_bf16 v[88:91], v[240:243], v[204:207], 0
	v_mfma_f32_16x16x32_bf16 v[56:59], v[236:239], v[148:151], v[56:59]
	v_mfma_f32_16x16x32_bf16 v[8:11], v[244:247], v[148:151], v[8:11]
	v_mfma_f32_16x16x32_bf16 v[52:55], v[236:239], v[156:159], v[52:55]
	v_mfma_f32_16x16x32_bf16 v[4:7], v[244:247], v[156:159], v[4:7]
	v_mfma_f32_16x16x32_bf16 v[48:51], v[236:239], v[164:167], v[48:51]
	v_mfma_f32_16x16x32_bf16 v[0:3], v[244:247], v[164:167], v[0:3]
	v_mfma_f32_16x16x32_bf16 v[100:103], v[236:239], v[208:211], v[100:103]
	v_mfma_f32_16x16x32_bf16 v[88:91], v[244:247], v[208:211], v[88:91]
	v_add_u32_e32 v140, 0x18000, v202
	s_barrier
	ds_read_b128 v[128:131], v140
	ds_read_b128 v[132:135], v140 offset:1024
	ds_read_b128 v[136:139], v140 offset:2048
	ds_read_b128 v[140:143], v140 offset:3072
	ds_read_b128 v[144:147], v203 offset:32768
	ds_read_b128 v[148:151], v203 offset:33792
	ds_read_b128 v[152:155], v203 offset:34816
	ds_read_b128 v[156:159], v203 offset:35840
	ds_read_b128 v[160:163], v203 offset:36864
	ds_read_b128 v[164:167], v203 offset:37888
	ds_read_b128 v[204:207], v203 offset:38912
	ds_read_b128 v[208:211], v203 offset:39936
	s_add_u32 s48, s82, 0x80000
	s_addc_u32 s49, s83, 0
	s_mov_b32 m0, s30
	s_nop 0
	global_load_lds_dwordx4 v168, s[48:49]
	s_add_u32 s48, s82, 0x82000
	s_addc_u32 s49, s83, 0
	s_mov_b32 m0, s34
	s_nop 0
	global_load_lds_dwordx4 v168, s[48:49]
	s_waitcnt lgkmcnt(8)
	s_waitcnt vmcnt(10)
	s_barrier
	s_waitcnt lgkmcnt(7)
	v_mfma_f32_16x16x32_bf16 v[96:99], v[128:131], v[144:147], v[96:99]
	v_mfma_f32_16x16x32_bf16 v[44:47], v[136:139], v[144:147], v[44:47]
	s_waitcnt lgkmcnt(5)
	v_mfma_f32_16x16x32_bf16 v[92:95], v[128:131], v[152:155], v[92:95]
	v_mfma_f32_16x16x32_bf16 v[40:43], v[136:139], v[152:155], v[40:43]
	s_waitcnt lgkmcnt(3)
	v_mfma_f32_16x16x32_bf16 v[84:87], v[128:131], v[160:163], v[84:87]
	v_mfma_f32_16x16x32_bf16 v[36:39], v[136:139], v[160:163], v[36:39]
	s_waitcnt lgkmcnt(1)
	v_mfma_f32_16x16x32_bf16 v[124:127], v[128:131], v[204:207], v[124:127]
	v_mfma_f32_16x16x32_bf16 v[120:123], v[136:139], v[204:207], v[120:123]
	v_mfma_f32_16x16x32_bf16 v[96:99], v[132:135], v[148:151], v[96:99]
	v_mfma_f32_16x16x32_bf16 v[44:47], v[140:143], v[148:151], v[44:47]
	v_mfma_f32_16x16x32_bf16 v[92:95], v[132:135], v[156:159], v[92:95]
	v_mfma_f32_16x16x32_bf16 v[40:43], v[140:143], v[156:159], v[40:43]
	v_mfma_f32_16x16x32_bf16 v[84:87], v[132:135], v[164:167], v[84:87]
	v_mfma_f32_16x16x32_bf16 v[36:39], v[140:143], v[164:167], v[36:39]
	s_waitcnt lgkmcnt(0)
	v_mfma_f32_16x16x32_bf16 v[124:127], v[132:135], v[208:211], v[124:127]
	v_mfma_f32_16x16x32_bf16 v[120:123], v[140:143], v[208:211], v[120:123]
	s_barrier
	v_add_u32_e32 v188, 0x1c000, v202
	ds_read_b128 v[212:215], v188
	ds_read_b128 v[236:239], v188 offset:1024
	ds_read_b128 v[240:243], v188 offset:2048
	ds_read_b128 v[244:247], v188 offset:3072
	s_add_u32 s48, s78, 0x4000
	s_addc_u32 s49, s79, 0
	s_mov_b32 m0, s38
	s_nop 0
	global_load_lds_dwordx4 v168, s[48:49]
	s_add_u32 s48, s78, 0x6000
	s_addc_u32 s49, s79, 0
	s_mov_b32 m0, s39
	s_nop 0
	global_load_lds_dwordx4 v168, s[48:49]
	s_waitcnt vmcnt(10)
	s_barrier
; #define PG8_STAGE(bufoff, gbase, hoff, imm) do { _Pragma("unroll") for (int _i = 0; _i < 2; ++_i) { \
;         asm volatile("s_mov_b32 m0, %0\n\ts_nop 0\n\tglobal_load_lds_dwordx4 %1, %2" \
;             :: "s"(lds0 + (unsigned)((bufoff) + _i * 8192)), "v"(voff0), "s"((const char*)(gbase) + (size_t)(hoff) + (size_t)(_i * 8192)) : "memory"); } } while (0)
; #define PG8_LDA(dst, b, h) do { _Pragma("unroll") for (int m = 0; m < 4; ++m) _Pragma("unroll") for (int k = 0; k < 2; ++k) dst[m][k] = *(const LAS bf16x8*)(lds + PG8_SA(b, h) + aoff + m * 2048 + k * 1024); } while (0)
; #define PG8_MMA(ai, bj, At, Bt) do { __builtin_amdgcn_s_setprio(1); _Pragma("unroll") for (int m = 0; m < 4; ++m) _Pragma("unroll") for (int n = 0; n < 2; ++n) _Pragma("unroll") for (int k = 0; k < 2; ++k) \
;         acc[ai][bj][m][n] = __builtin_amdgcn_mfma_f32_16x16x32_bf16(Bt[n][k], At[m][k], acc[ai][bj][m][n], 0, 0, 0); __builtin_amdgcn_s_setprio(0); } while (0)
; #define PG8_WAIT_V(n) asm volatile("s_waitcnt vmcnt(" #n ")" ::: "memory")
; #define PG8_WAIT_L(n) asm volatile("s_waitcnt lgkmcnt(" #n ")" ::: "memory")
; #define PG8_BAR __builtin_amdgcn_s_barrier()
; #define PG8_SCHED __builtin_amdgcn_sched_barrier(0)
; template <class Epi>
; __device__ __forceinline__ void gemm_phase(LAS unsigned char* lds, const Gemm g, const StaticOrder& S, const Epi& E) {
;     ...
;             PG8_LDA(At, 1, 1); PG8_STAGE(PG8_SA(1, 0), a2 + KS, 0, 0);
;             PG8_BAR; PG8_WAIT_L(0); PG8_MMA(1, 0, At, B0); PG8_BAR; PG8_SCHED;
;             PG8_STAGE(PG8_SB(1, 1), b2 + KS, hB, 0);
;             PG8_WAIT_V(6); PG8_BAR; PG8_MMA(1, 1, At, B1); PG8_BAR;
	s_waitcnt lgkmcnt(3)
	v_mfma_f32_16x16x32_bf16 v[80:83], v[212:215], v[144:147], v[80:83]
	s_waitcnt lgkmcnt(1)
	v_mfma_f32_16x16x32_bf16 v[32:35], v[240:243], v[144:147], v[32:35]
	v_mfma_f32_16x16x32_bf16 v[76:79], v[212:215], v[152:155], v[76:79]
	v_mfma_f32_16x16x32_bf16 v[28:31], v[240:243], v[152:155], v[28:31]
	v_mfma_f32_16x16x32_bf16 v[72:75], v[212:215], v[160:163], v[72:75]
	v_mfma_f32_16x16x32_bf16 v[24:27], v[240:243], v[160:163], v[24:27]
	v_mfma_f32_16x16x32_bf16 v[116:119], v[212:215], v[204:207], v[116:119]
	v_mfma_f32_16x16x32_bf16 v[112:115], v[240:243], v[204:207], v[112:115]
	v_mfma_f32_16x16x32_bf16 v[80:83], v[236:239], v[148:151], v[80:83]
	s_waitcnt lgkmcnt(0)
	v_mfma_f32_16x16x32_bf16 v[32:35], v[244:247], v[148:151], v[32:35]
	v_mfma_f32_16x16x32_bf16 v[76:79], v[236:239], v[156:159], v[76:79]
	v_mfma_f32_16x16x32_bf16 v[28:31], v[244:247], v[156:159], v[28:31]
	v_mfma_f32_16x16x32_bf16 v[72:75], v[236:239], v[164:167], v[72:75]
	v_mfma_f32_16x16x32_bf16 v[24:27], v[244:247], v[164:167], v[24:27]
	v_mfma_f32_16x16x32_bf16 v[116:119], v[236:239], v[208:211], v[116:119]
	v_mfma_f32_16x16x32_bf16 v[112:115], v[244:247], v[208:211], v[112:115]
	s_barrier
	ds_read_b128 v[144:147], v203 offset:49152
	ds_read_b128 v[148:151], v203 offset:50176
	ds_read_b128 v[152:155], v203 offset:51200
	ds_read_b128 v[156:159], v203 offset:52224
	ds_read_b128 v[160:163], v203 offset:53248
	ds_read_b128 v[164:167], v203 offset:54272
	ds_read_b128 v[204:207], v203 offset:55296
	ds_read_b128 v[208:211], v203 offset:56320
	s_add_u32 s48, s82, 0x4000
	s_addc_u32 s49, s83, 0
	s_mov_b32 m0, s40
	s_nop 0
	global_load_lds_dwordx4 v168, s[48:49]
	s_add_u32 s48, s82, 0x6000
	s_addc_u32 s49, s83, 0
	s_mov_b32 m0, s41
	s_nop 0
	global_load_lds_dwordx4 v168, s[48:49]
	s_barrier
	s_waitcnt lgkmcnt(7)
	v_mfma_f32_16x16x32_bf16 v[68:71], v[128:131], v[144:147], v[68:71]
	v_mfma_f32_16x16x32_bf16 v[20:23], v[136:139], v[144:147], v[20:23]
	s_waitcnt lgkmcnt(5)
	v_mfma_f32_16x16x32_bf16 v[64:67], v[128:131], v[152:155], v[64:67]
	v_mfma_f32_16x16x32_bf16 v[16:19], v[136:139], v[152:155], v[16:19]
	s_waitcnt lgkmcnt(3)
	v_mfma_f32_16x16x32_bf16 v[60:63], v[128:131], v[160:163], v[60:63]
	v_mfma_f32_16x16x32_bf16 v[12:15], v[136:139], v[160:163], v[12:15]
	s_waitcnt lgkmcnt(1)
	v_mfma_f32_16x16x32_bf16 v[108:111], v[128:131], v[204:207], v[108:111]
	v_mfma_f32_16x16x32_bf16 v[104:107], v[136:139], v[204:207], v[104:107]
	v_mfma_f32_16x16x32_bf16 v[68:71], v[132:135], v[148:151], v[68:71]
	v_mfma_f32_16x16x32_bf16 v[20:23], v[140:143], v[148:151], v[20:23]
	v_mfma_f32_16x16x32_bf16 v[64:67], v[132:135], v[156:159], v[64:67]
	v_mfma_f32_16x16x32_bf16 v[16:19], v[140:143], v[156:159], v[16:19]
	v_mfma_f32_16x16x32_bf16 v[60:63], v[132:135], v[164:167], v[60:63]
	v_mfma_f32_16x16x32_bf16 v[12:15], v[140:143], v[164:167], v[12:15]
	s_waitcnt lgkmcnt(0)
	v_mfma_f32_16x16x32_bf16 v[108:111], v[132:135], v[208:211], v[108:111]
	v_mfma_f32_16x16x32_bf16 v[104:107], v[140:143], v[208:211], v[104:107]
	s_barrier
	s_add_u32 s48, s78, 0x84000
	s_addc_u32 s49, s79, 0
	s_mov_b32 m0, s42
	s_nop 0
	global_load_lds_dwordx4 v168, s[48:49]
	s_add_u32 s48, s78, 0x86000
	s_addc_u32 s49, s79, 0
	s_mov_b32 m0, s43
	s_nop 0
	global_load_lds_dwordx4 v168, s[48:49]
	s_waitcnt vmcnt(10)
	s_barrier
	v_mfma_f32_16x16x32_bf16 v[56:59], v[212:215], v[144:147], v[56:59]
	v_mfma_f32_16x16x32_bf16 v[8:11], v[240:243], v[144:147], v[8:11]
	v_mfma_f32_16x16x32_bf16 v[52:55], v[212:215], v[152:155], v[52:55]
	v_mfma_f32_16x16x32_bf16 v[4:7], v[240:243], v[152:155], v[4:7]
	v_mfma_f32_16x16x32_bf16 v[48:51], v[212:215], v[160:163], v[48:51]
	v_mfma_f32_16x16x32_bf16 v[0:3], v[240:243], v[160:163], v[0:3]
	v_mfma_f32_16x16x32_bf16 v[100:103], v[212:215], v[204:207], v[100:103]
	v_mfma_f32_16x16x32_bf16 v[88:91], v[240:243], v[204:207], v[88:91]
	v_mfma_f32_16x16x32_bf16 v[56:59], v[236:239], v[148:151], v[56:59]
	v_mfma_f32_16x16x32_bf16 v[8:11], v[244:247], v[148:151], v[8:11]
	v_mfma_f32_16x16x32_bf16 v[52:55], v[236:239], v[156:159], v[52:55]
	v_mfma_f32_16x16x32_bf16 v[4:7], v[244:247], v[156:159], v[4:7]
	v_mfma_f32_16x16x32_bf16 v[48:51], v[236:239], v[164:167], v[48:51]
	v_mfma_f32_16x16x32_bf16 v[0:3], v[244:247], v[164:167], v[0:3]
	v_mfma_f32_16x16x32_bf16 v[100:103], v[236:239], v[208:211], v[100:103]
	v_mfma_f32_16x16x32_bf16 v[88:91], v[244:247], v[208:211], v[88:91]
	s_add_i32 s0, s0, 2
	s_add_u32 s9, s9, 0x8000
	s_addc_u32 s63, s63, 0
	s_cmp_gt_u32 s0, 29
	s_mov_b64 s[78:79], s[80:81]
	s_barrier
	s_branch .LBB0_507

; #define PG8_STAGE(bufoff, gbase, hoff, imm) do { _Pragma("unroll") for (int _i = 0; _i < 2; ++_i) { \
;         asm volatile("s_mov_b32 m0, %0\n\ts_nop 0\n\tglobal_load_lds_dwordx4 %1, %2" \
;             :: "s"(lds0 + (unsigned)((bufoff) + _i * 8192)), "v"(voff0), "s"((const char*)(gbase) + (size_t)(hoff) + (size_t)(_i * 8192)) : "memory"); } } while (0)
; #define PG8_LDA(dst, b, h) do { _Pragma("unroll") for (int m = 0; m < 4; ++m) _Pragma("unroll") for (int k = 0; k < 2; ++k) dst[m][k] = *(const LAS bf16x8*)(lds + PG8_SA(b, h) + aoff + m * 2048 + k * 1024); } while (0)
; #define PG8_LDB(dst, b, h) do { _Pragma("unroll") for (int n = 0; n < 2; ++n) _Pragma("unroll") for (int k = 0; k < 2; ++k) dst[n][k] = *(const LAS bf16x8*)(lds + PG8_SB(b, h) + boff + n * 2048 + k * 1024); } while (0)
; #define PG8_WAIT_V(n) asm volatile("s_waitcnt vmcnt(" #n ")" ::: "memory")
; #define PG8_WAIT_L(n) asm volatile("s_waitcnt lgkmcnt(" #n ")" ::: "memory")
; #define PG8_BAR __builtin_amdgcn_s_barrier()
; template <class Epi>
; __device__ __forceinline__ void gemm_phase(LAS unsigned char* lds, const Gemm g, const StaticOrder& S, const Epi& E) {
;     ...
;         const bool has_next = S.next(ui + 1, nxt);
;         const char* nA = has_next ? (const char*)g.A + (size_t)nxt.pm * tstepA + (size_t)(nxt.pn >> g.gshift) * g.gstride : cA;
;         const char* nB = has_next ? (const char*)g.Bt + (size_t)nxt.pn * tstepB : cB;
;         for (int t = 0; t < nt; t += 2) {
;             const bool last = (t == nt - 2);
;             if (last) E.pre(cur, wid, lane, (unsigned)(size_t)(lds + STAGE_BYTES));
;             const char* aT = cA + (size_t)t * KS;
;             const char* a2 = last ? nA : aT + 2 * KS; const char* b2 = last ? nB : cB + (size_t)(t + 2) * KS;
;             PG8_LDB(B0, 0, 0); PG8_SCHED; PG8_LDA(At, 0, 0); PG8_STAGE(PG8_SA(1, 1), aT + KS, hA, 0);
;             PG8_WAIT_L(8); PG8_BAR; PG8_WAIT_L(0); PG8_MMA(0, 0, At, B0); PG8_BAR; PG8_SCHED;
;             PG8_LDB(B1, 0, 1); PG8_STAGE(PG8_SB(0, 0), b2, 0, 0);
;             PG8_BAR; PG8_WAIT_L(0); PG8_MMA(0, 1, At, B1); PG8_BAR;
;             PG8_LDA(At, 0, 1); PG8_STAGE(PG8_SA(0, 0), a2, 0, 0);
;             PG8_BAR; PG8_WAIT_L(0); PG8_MMA(1, 0, At, B0); PG8_BAR; PG8_SCHED;
;             PG8_STAGE(PG8_SB(0, 1), b2, hB, 0);
;             PG8_WAIT_V(6); PG8_BAR; PG8_MMA(1, 1, At, B1); PG8_BAR;
.LBB0_609:
	s_ashr_i32 s55, s54, 31
	s_lshl_b64 s[0:1], s[54:55], 20
	v_cmp_lt_i64_e32 vcc, s[56:57], v[192:193]
	s_add_u32 s56, s6, s0
	s_addc_u32 s57, s7, s1
	s_and_b64 s[0:1], vcc, exec
	s_cselect_b32 s0, s57, s61
	s_cselect_b32 s1, s56, s60
	s_ashr_i32 s53, s52, 31
	s_lshl_b64 s[48:49], s[52:53], 20
	s_add_u32 s58, s17, s48
	s_addc_u32 s59, s21, s49
	s_and_b64 s[48:49], vcc, exec
	s_cselect_b32 s53, s59, s63
	s_cselect_b32 s55, s58, s62
	s_add_u32 s69, s62, 0x8000
	s_addc_u32 s70, s63, 0
	s_mov_b32 s71, -2
	s_waitcnt vmcnt(16)
	s_add_u32 s62, s60, 0x8000
	v_add_u32_e32 v132, 0x10000, v236
	s_addc_u32 s63, s61, 0
	ds_read_b128 v[120:123], v132
	ds_read_b128 v[124:127], v132 offset:1024
	ds_read_b128 v[128:131], v132 offset:2048
	ds_read_b128 v[132:135], v132 offset:3072
	s_add_u32 s48, s60, 0x84000
	s_addc_u32 s49, s61, 0
	s_add_u32 s64, s60, 0x86000
	s_addc_u32 s65, s61, 0
	s_cmp_eq_u32 s71, 28
	s_cselect_b32 s61, s0, s63
	s_cselect_b32 s60, s1, s62
	ds_read_b128 v[136:139], v237
	ds_read_b128 v[140:143], v237 offset:1024
	ds_read_b128 v[152:155], v237 offset:2048
	ds_read_b128 v[156:159], v237 offset:3072
	ds_read_b128 v[160:163], v237 offset:4096
	ds_read_b128 v[164:167], v237 offset:5120
	ds_read_b128 v[168:171], v237 offset:6144
	ds_read_b128 v[172:175], v237 offset:7168
	s_mov_b32 m0, s67
	s_nop 0
	global_load_lds_dwordx4 v188, s[48:49]
	s_mov_b32 m0, s68
	s_nop 0
	global_load_lds_dwordx4 v188, s[64:65]
	s_waitcnt lgkmcnt(8)
	s_waitcnt vmcnt(10)
	s_barrier
	s_waitcnt lgkmcnt(7)
	v_mfma_f32_16x16x32_bf16 v[148:151], v[120:123], v[136:139], 0
	v_mfma_f32_16x16x32_bf16 v[144:147], v[128:131], v[136:139], 0
	s_waitcnt lgkmcnt(5)
	v_mfma_f32_16x16x32_bf16 v[108:111], v[120:123], v[152:155], 0
	v_mfma_f32_16x16x32_bf16 v[104:107], v[128:131], v[152:155], 0
	s_waitcnt lgkmcnt(3)
	v_mfma_f32_16x16x32_bf16 v[92:95], v[120:123], v[160:163], 0
	v_mfma_f32_16x16x32_bf16 v[88:91], v[128:131], v[160:163], 0
	s_waitcnt lgkmcnt(1)
	v_mfma_f32_16x16x32_bf16 v[76:79], v[120:123], v[168:171], 0
	v_mfma_f32_16x16x32_bf16 v[72:75], v[128:131], v[168:171], 0
	v_mfma_f32_16x16x32_bf16 v[148:151], v[124:127], v[140:143], v[148:151]
	v_mfma_f32_16x16x32_bf16 v[144:147], v[132:135], v[140:143], v[144:147]
	v_mfma_f32_16x16x32_bf16 v[108:111], v[124:127], v[156:159], v[108:111]
	v_mfma_f32_16x16x32_bf16 v[104:107], v[132:135], v[156:159], v[104:107]
	v_mfma_f32_16x16x32_bf16 v[92:95], v[124:127], v[164:167], v[92:95]
	v_mfma_f32_16x16x32_bf16 v[88:91], v[132:135], v[164:167], v[88:91]
	s_waitcnt lgkmcnt(0)
	v_mfma_f32_16x16x32_bf16 v[76:79], v[124:127], v[172:175], v[76:79]
	v_mfma_f32_16x16x32_bf16 v[72:75], v[132:135], v[172:175], v[72:75]
	s_barrier
	v_add_u32_e32 v200, 0x14000, v236
	ds_read_b128 v[176:179], v200
	ds_read_b128 v[180:183], v200 offset:1024
	ds_read_b128 v[184:187], v200 offset:2048
	ds_read_b128 v[200:203], v200 offset:3072
	s_cselect_b32 s64, s55, s69
	s_cselect_b32 s65, s53, s70
	s_mov_b32 m0, s24
	s_nop 0
	global_load_lds_dwordx4 v188, s[64:65]
	s_add_u32 s48, s64, 0x2000
	s_addc_u32 s49, s65, 0
	s_mov_b32 m0, s25
	s_nop 0
	global_load_lds_dwordx4 v188, s[48:49]
	s_waitcnt vmcnt(10)
	s_barrier
	s_waitcnt lgkmcnt(3)
	v_mfma_f32_16x16x32_bf16 v[116:119], v[176:179], v[136:139], 0
	s_waitcnt lgkmcnt(1)
	v_mfma_f32_16x16x32_bf16 v[112:115], v[184:187], v[136:139], 0
	v_mfma_f32_16x16x32_bf16 v[100:103], v[176:179], v[152:155], 0
	v_mfma_f32_16x16x32_bf16 v[96:99], v[184:187], v[152:155], 0
	v_mfma_f32_16x16x32_bf16 v[84:87], v[176:179], v[160:163], 0
	v_mfma_f32_16x16x32_bf16 v[80:83], v[184:187], v[160:163], 0
	v_mfma_f32_16x16x32_bf16 v[68:71], v[176:179], v[168:171], 0
	v_mfma_f32_16x16x32_bf16 v[64:67], v[184:187], v[168:171], 0
	v_mfma_f32_16x16x32_bf16 v[116:119], v[180:183], v[140:143], v[116:119]
	s_waitcnt lgkmcnt(0)
	v_mfma_f32_16x16x32_bf16 v[112:115], v[200:203], v[140:143], v[112:115]
	v_mfma_f32_16x16x32_bf16 v[100:103], v[180:183], v[156:159], v[100:103]
	v_mfma_f32_16x16x32_bf16 v[96:99], v[200:203], v[156:159], v[96:99]
	v_mfma_f32_16x16x32_bf16 v[84:87], v[180:183], v[164:167], v[84:87]
	v_mfma_f32_16x16x32_bf16 v[80:83], v[200:203], v[164:167], v[80:83]
	v_mfma_f32_16x16x32_bf16 v[68:71], v[180:183], v[172:175], v[68:71]
	v_mfma_f32_16x16x32_bf16 v[64:67], v[200:203], v[172:175], v[64:67]
	s_barrier
	ds_read_b128 v[136:139], v237 offset:16384
	ds_read_b128 v[140:143], v237 offset:17408
	ds_read_b128 v[152:155], v237 offset:18432
	ds_read_b128 v[156:159], v237 offset:19456
	ds_read_b128 v[160:163], v237 offset:20480
	ds_read_b128 v[164:167], v237 offset:21504
	ds_read_b128 v[168:171], v237 offset:22528
	ds_read_b128 v[172:175], v237 offset:23552
	s_mov_b32 m0, s22
	s_nop 0
	global_load_lds_dwordx4 v188, s[60:61]
	s_add_u32 s48, s60, 0x2000
	s_addc_u32 s49, s61, 0
	s_mov_b32 m0, s26
	s_nop 0
	global_load_lds_dwordx4 v188, s[48:49]
	s_barrier
	s_waitcnt lgkmcnt(7)
	v_mfma_f32_16x16x32_bf16 v[60:63], v[120:123], v[136:139], 0
	v_mfma_f32_16x16x32_bf16 v[56:59], v[128:131], v[136:139], 0
	s_waitcnt lgkmcnt(5)
	v_mfma_f32_16x16x32_bf16 v[44:47], v[120:123], v[152:155], 0
	v_mfma_f32_16x16x32_bf16 v[40:43], v[128:131], v[152:155], 0
	s_waitcnt lgkmcnt(3)
	v_mfma_f32_16x16x32_bf16 v[28:31], v[120:123], v[160:163], 0
	v_mfma_f32_16x16x32_bf16 v[24:27], v[128:131], v[160:163], 0
	s_waitcnt lgkmcnt(1)
	v_mfma_f32_16x16x32_bf16 v[12:15], v[120:123], v[168:171], 0
	v_mfma_f32_16x16x32_bf16 v[8:11], v[128:131], v[168:171], 0
	v_mfma_f32_16x16x32_bf16 v[60:63], v[124:127], v[140:143], v[60:63]
	v_mfma_f32_16x16x32_bf16 v[56:59], v[132:135], v[140:143], v[56:59]
	v_mfma_f32_16x16x32_bf16 v[44:47], v[124:127], v[156:159], v[44:47]
	v_mfma_f32_16x16x32_bf16 v[40:43], v[132:135], v[156:159], v[40:43]
	v_mfma_f32_16x16x32_bf16 v[28:31], v[124:127], v[164:167], v[28:31]
	v_mfma_f32_16x16x32_bf16 v[24:27], v[132:135], v[164:167], v[24:27]
	s_waitcnt lgkmcnt(0)
	v_mfma_f32_16x16x32_bf16 v[12:15], v[124:127], v[172:175], v[12:15]
	v_mfma_f32_16x16x32_bf16 v[8:11], v[132:135], v[172:175], v[8:11]
	s_barrier
; #define PG8_STAGE(bufoff, gbase, hoff, imm) do { _Pragma("unroll") for (int _i = 0; _i < 2; ++_i) { \
;         asm volatile("s_mov_b32 m0, %0\n\ts_nop 0\n\tglobal_load_lds_dwordx4 %1, %2" \
;             :: "s"(lds0 + (unsigned)((bufoff) + _i * 8192)), "v"(voff0), "s"((const char*)(gbase) + (size_t)(hoff) + (size_t)(_i * 8192)) : "memory"); } } while (0)
; #define PG8_LDA(dst, b, h) do { _Pragma("unroll") for (int m = 0; m < 4; ++m) _Pragma("unroll") for (int k = 0; k < 2; ++k) dst[m][k] = *(const LAS bf16x8*)(lds + PG8_SA(b, h) + aoff + m * 2048 + k * 1024); } while (0)
; #define PG8_LDB(dst, b, h) do { _Pragma("unroll") for (int n = 0; n < 2; ++n) _Pragma("unroll") for (int k = 0; k < 2; ++k) dst[n][k] = *(const LAS bf16x8*)(lds + PG8_SB(b, h) + boff + n * 2048 + k * 1024); } while (0)
; #define PG8_MMA(ai, bj, At, Bt) do { __builtin_amdgcn_s_setprio(1); _Pragma("unroll") for (int m = 0; m < 4; ++m) _Pragma("unroll") for (int n = 0; n < 2; ++n) _Pragma("unroll") for (int k = 0; k < 2; ++k) \
;         acc[ai][bj][m][n] = __builtin_amdgcn_mfma_f32_16x16x32_bf16(Bt[n][k], At[m][k], acc[ai][bj][m][n], 0, 0, 0); __builtin_amdgcn_s_setprio(0); } while (0)
; #define PG8_WAIT_V(n) asm volatile("s_waitcnt vmcnt(" #n ")" ::: "memory")
; #define PG8_WAIT_L(n) asm volatile("s_waitcnt lgkmcnt(" #n ")" ::: "memory")
; #define PG8_BAR __builtin_amdgcn_s_barrier()
; #define PG8_SCHED __builtin_amdgcn_sched_barrier(0)
; template <class Epi>
; __device__ __forceinline__ void gemm_phase(LAS unsigned char* lds, const Gemm g, const StaticOrder& S, const Epi& E) {
;     ...
;             PG8_STAGE(PG8_SB(0, 1), b2, hB, 0);
;             PG8_WAIT_V(6); PG8_BAR; PG8_MMA(1, 1, At, B1); PG8_BAR;
;             PG8_LDB(B0, 1, 0); PG8_SCHED; PG8_LDA(At, 1, 0); PG8_STAGE(PG8_SA(0, 1), a2, hA, 0);
;             PG8_WAIT_L(8); PG8_BAR; PG8_WAIT_L(0); PG8_MMA(0, 0, At, B0); PG8_BAR; PG8_SCHED;
;             PG8_LDB(B1, 1, 1); PG8_STAGE(PG8_SB(1, 0), b2 + KS, 0, 0);
;             PG8_BAR; PG8_WAIT_L(0); PG8_MMA(0, 1, At, B1); PG8_BAR;
;             PG8_LDA(At, 1, 1); PG8_STAGE(PG8_SA(1, 0), a2 + KS, 0, 0);
	s_add_u32 s48, s64, 0x80000
	s_addc_u32 s49, s65, 0
	s_mov_b32 m0, s27
	s_nop 0
	global_load_lds_dwordx4 v188, s[48:49]
	s_add_u32 s48, s64, 0x82000
	s_addc_u32 s49, s65, 0
	s_mov_b32 m0, s28
	s_nop 0
	global_load_lds_dwordx4 v188, s[48:49]
	s_waitcnt vmcnt(10)
	s_barrier
	v_mfma_f32_16x16x32_bf16 v[52:55], v[176:179], v[136:139], 0
	v_mfma_f32_16x16x32_bf16 v[48:51], v[184:187], v[136:139], 0
	v_mfma_f32_16x16x32_bf16 v[36:39], v[176:179], v[152:155], 0
	v_mfma_f32_16x16x32_bf16 v[32:35], v[184:187], v[152:155], 0
	v_mfma_f32_16x16x32_bf16 v[20:23], v[176:179], v[160:163], 0
	v_mfma_f32_16x16x32_bf16 v[16:19], v[184:187], v[160:163], 0
	v_mfma_f32_16x16x32_bf16 v[4:7], v[176:179], v[168:171], 0
	v_mfma_f32_16x16x32_bf16 v[0:3], v[184:187], v[168:171], 0
	v_mfma_f32_16x16x32_bf16 v[52:55], v[180:183], v[140:143], v[52:55]
	v_mfma_f32_16x16x32_bf16 v[48:51], v[200:203], v[140:143], v[48:51]
	v_mfma_f32_16x16x32_bf16 v[36:39], v[180:183], v[156:159], v[36:39]
	v_mfma_f32_16x16x32_bf16 v[32:35], v[200:203], v[156:159], v[32:35]
	v_mfma_f32_16x16x32_bf16 v[20:23], v[180:183], v[164:167], v[20:23]
	v_mfma_f32_16x16x32_bf16 v[16:19], v[200:203], v[164:167], v[16:19]
	v_mfma_f32_16x16x32_bf16 v[4:7], v[180:183], v[172:175], v[4:7]
	v_mfma_f32_16x16x32_bf16 v[0:3], v[200:203], v[172:175], v[0:3]
	v_add_u32_e32 v132, 0x18000, v236
	s_barrier
	ds_read_b128 v[120:123], v132
	ds_read_b128 v[124:127], v132 offset:1024
	ds_read_b128 v[128:131], v132 offset:2048
	ds_read_b128 v[132:135], v132 offset:3072
	ds_read_b128 v[136:139], v237 offset:32768
	ds_read_b128 v[140:143], v237 offset:33792
	ds_read_b128 v[152:155], v237 offset:34816
	ds_read_b128 v[156:159], v237 offset:35840
	ds_read_b128 v[160:163], v237 offset:36864
	ds_read_b128 v[164:167], v237 offset:37888
	ds_read_b128 v[168:171], v237 offset:38912
	ds_read_b128 v[172:175], v237 offset:39936
	s_add_u32 s48, s60, 0x80000
	s_addc_u32 s49, s61, 0
	s_mov_b32 m0, s29
	s_nop 0
	global_load_lds_dwordx4 v188, s[48:49]
	s_add_u32 s48, s60, 0x82000
	s_addc_u32 s49, s61, 0
	s_mov_b32 m0, s30
	s_nop 0
	global_load_lds_dwordx4 v188, s[48:49]
	s_waitcnt lgkmcnt(8)
	s_waitcnt vmcnt(10)
	s_barrier
	s_waitcnt lgkmcnt(7)
	v_mfma_f32_16x16x32_bf16 v[148:151], v[120:123], v[136:139], v[148:151]
	v_mfma_f32_16x16x32_bf16 v[144:147], v[128:131], v[136:139], v[144:147]
	s_waitcnt lgkmcnt(5)
	v_mfma_f32_16x16x32_bf16 v[108:111], v[120:123], v[152:155], v[108:111]
	v_mfma_f32_16x16x32_bf16 v[104:107], v[128:131], v[152:155], v[104:107]
	s_waitcnt lgkmcnt(3)
	v_mfma_f32_16x16x32_bf16 v[92:95], v[120:123], v[160:163], v[92:95]
	v_mfma_f32_16x16x32_bf16 v[88:91], v[128:131], v[160:163], v[88:91]
	s_waitcnt lgkmcnt(1)
	v_mfma_f32_16x16x32_bf16 v[76:79], v[120:123], v[168:171], v[76:79]
	v_mfma_f32_16x16x32_bf16 v[72:75], v[128:131], v[168:171], v[72:75]
	v_mfma_f32_16x16x32_bf16 v[148:151], v[124:127], v[140:143], v[148:151]
	v_mfma_f32_16x16x32_bf16 v[144:147], v[132:135], v[140:143], v[144:147]
	v_mfma_f32_16x16x32_bf16 v[108:111], v[124:127], v[156:159], v[108:111]
	v_mfma_f32_16x16x32_bf16 v[104:107], v[132:135], v[156:159], v[104:107]
	v_mfma_f32_16x16x32_bf16 v[92:95], v[124:127], v[164:167], v[92:95]
	v_mfma_f32_16x16x32_bf16 v[88:91], v[132:135], v[164:167], v[88:91]
	s_waitcnt lgkmcnt(0)
	v_mfma_f32_16x16x32_bf16 v[76:79], v[124:127], v[172:175], v[76:79]
	v_mfma_f32_16x16x32_bf16 v[72:75], v[132:135], v[172:175], v[72:75]
	s_barrier
	v_add_u32_e32 v200, 0x1c000, v236
	ds_read_b128 v[176:179], v200
	ds_read_b128 v[180:183], v200 offset:1024
	ds_read_b128 v[184:187], v200 offset:2048
	ds_read_b128 v[200:203], v200 offset:3072
	s_add_u32 s48, s64, 0x4000
	s_addc_u32 s49, s65, 0
	s_mov_b32 m0, s39
	s_nop 0
	global_load_lds_dwordx4 v188, s[48:49]
	s_add_u32 s48, s64, 0x6000
	s_addc_u32 s49, s65, 0
	s_mov_b32 m0, s40
	s_nop 0
	global_load_lds_dwordx4 v188, s[48:49]
	s_waitcnt vmcnt(10)
	s_barrier
; #define PG8_STAGE(bufoff, gbase, hoff, imm) do { _Pragma("unroll") for (int _i = 0; _i < 2; ++_i) { \
;         asm volatile("s_mov_b32 m0, %0\n\ts_nop 0\n\tglobal_load_lds_dwordx4 %1, %2" \
;             :: "s"(lds0 + (unsigned)((bufoff) + _i * 8192)), "v"(voff0), "s"((const char*)(gbase) + (size_t)(hoff) + (size_t)(_i * 8192)) : "memory"); } } while (0)
; #define PG8_LDA(dst, b, h) do { _Pragma("unroll") for (int m = 0; m < 4; ++m) _Pragma("unroll") for (int k = 0; k < 2; ++k) dst[m][k] = *(const LAS bf16x8*)(lds + PG8_SA(b, h) + aoff + m * 2048 + k * 1024); } while (0)
; #define PG8_LDB(dst, b, h) do { _Pragma("unroll") for (int n = 0; n < 2; ++n) _Pragma("unroll") for (int k = 0; k < 2; ++k) dst[n][k] = *(const LAS bf16x8*)(lds + PG8_SB(b, h) + boff + n * 2048 + k * 1024); } while (0)
; #define PG8_MMA(ai, bj, At, Bt) do { __builtin_amdgcn_s_setprio(1); _Pragma("unroll") for (int m = 0; m < 4; ++m) _Pragma("unroll") for (int n = 0; n < 2; ++n) _Pragma("unroll") for (int k = 0; k < 2; ++k) \
;         acc[ai][bj][m][n] = __builtin_amdgcn_mfma_f32_16x16x32_bf16(Bt[n][k], At[m][k], acc[ai][bj][m][n], 0, 0, 0); __builtin_amdgcn_s_setprio(0); } while (0)
; #define PG8_WAIT_V(n) asm volatile("s_waitcnt vmcnt(" #n ")" ::: "memory")
; #define PG8_WAIT_L(n) asm volatile("s_waitcnt lgkmcnt(" #n ")" ::: "memory")
; #define PG8_BAR __builtin_amdgcn_s_barrier()
; #define PG8_SCHED __builtin_amdgcn_sched_barrier(0)
; template <class Epi>
; __device__ __forceinline__ void gemm_phase(LAS unsigned char* lds, const Gemm g, const StaticOrder& S, const Epi& E) {
;     ...
;             PG8_LDB(B1, 1, 1); PG8_STAGE(PG8_SB(1, 0), b2 + KS, 0, 0);
;             PG8_BAR; PG8_WAIT_L(0); PG8_MMA(0, 1, At, B1); PG8_BAR;
;             PG8_LDA(At, 1, 1); PG8_STAGE(PG8_SA(1, 0), a2 + KS, 0, 0);
;             PG8_BAR; PG8_WAIT_L(0); PG8_MMA(1, 0, At, B0); PG8_BAR; PG8_SCHED;
;             PG8_STAGE(PG8_SB(1, 1), b2 + KS, hB, 0);
;             PG8_WAIT_V(6); PG8_BAR; PG8_MMA(1, 1, At, B1); PG8_BAR;
	s_waitcnt lgkmcnt(3)
	v_mfma_f32_16x16x32_bf16 v[116:119], v[176:179], v[136:139], v[116:119]
	s_waitcnt lgkmcnt(1)
	v_mfma_f32_16x16x32_bf16 v[112:115], v[184:187], v[136:139], v[112:115]
	v_mfma_f32_16x16x32_bf16 v[100:103], v[176:179], v[152:155], v[100:103]
	v_mfma_f32_16x16x32_bf16 v[96:99], v[184:187], v[152:155], v[96:99]
	v_mfma_f32_16x16x32_bf16 v[84:87], v[176:179], v[160:163], v[84:87]
	v_mfma_f32_16x16x32_bf16 v[80:83], v[184:187], v[160:163], v[80:83]
	v_mfma_f32_16x16x32_bf16 v[68:71], v[176:179], v[168:171], v[68:71]
	v_mfma_f32_16x16x32_bf16 v[64:67], v[184:187], v[168:171], v[64:67]
	v_mfma_f32_16x16x32_bf16 v[116:119], v[180:183], v[140:143], v[116:119]
	s_waitcnt lgkmcnt(0)
	v_mfma_f32_16x16x32_bf16 v[112:115], v[200:203], v[140:143], v[112:115]
	v_mfma_f32_16x16x32_bf16 v[100:103], v[180:183], v[156:159], v[100:103]
	v_mfma_f32_16x16x32_bf16 v[96:99], v[200:203], v[156:159], v[96:99]
	v_mfma_f32_16x16x32_bf16 v[84:87], v[180:183], v[164:167], v[84:87]
	v_mfma_f32_16x16x32_bf16 v[80:83], v[200:203], v[164:167], v[80:83]
	v_mfma_f32_16x16x32_bf16 v[68:71], v[180:183], v[172:175], v[68:71]
	v_mfma_f32_16x16x32_bf16 v[64:67], v[200:203], v[172:175], v[64:67]
	s_barrier
	ds_read_b128 v[136:139], v237 offset:49152
	ds_read_b128 v[140:143], v237 offset:50176
	ds_read_b128 v[152:155], v237 offset:51200
	ds_read_b128 v[156:159], v237 offset:52224
	ds_read_b128 v[160:163], v237 offset:53248
	ds_read_b128 v[164:167], v237 offset:54272
	ds_read_b128 v[168:171], v237 offset:55296
	ds_read_b128 v[172:175], v237 offset:56320
	s_add_u32 s48, s60, 0x4000
	s_addc_u32 s49, s61, 0
	s_mov_b32 m0, s41
	s_nop 0
	global_load_lds_dwordx4 v188, s[48:49]
	s_add_u32 s48, s60, 0x6000
	s_addc_u32 s49, s61, 0
	s_mov_b32 m0, s42
	s_nop 0
	global_load_lds_dwordx4 v188, s[48:49]
	s_barrier
	s_waitcnt lgkmcnt(7)
	v_mfma_f32_16x16x32_bf16 v[60:63], v[120:123], v[136:139], v[60:63]
	v_mfma_f32_16x16x32_bf16 v[56:59], v[128:131], v[136:139], v[56:59]
	s_waitcnt lgkmcnt(5)
	v_mfma_f32_16x16x32_bf16 v[44:47], v[120:123], v[152:155], v[44:47]
	v_mfma_f32_16x16x32_bf16 v[40:43], v[128:131], v[152:155], v[40:43]
	s_waitcnt lgkmcnt(3)
	v_mfma_f32_16x16x32_bf16 v[28:31], v[120:123], v[160:163], v[28:31]
	v_mfma_f32_16x16x32_bf16 v[24:27], v[128:131], v[160:163], v[24:27]
	s_waitcnt lgkmcnt(1)
	v_mfma_f32_16x16x32_bf16 v[12:15], v[120:123], v[168:171], v[12:15]
	v_mfma_f32_16x16x32_bf16 v[8:11], v[128:131], v[168:171], v[8:11]
	v_mfma_f32_16x16x32_bf16 v[60:63], v[124:127], v[140:143], v[60:63]
	v_mfma_f32_16x16x32_bf16 v[56:59], v[132:135], v[140:143], v[56:59]
	v_mfma_f32_16x16x32_bf16 v[44:47], v[124:127], v[156:159], v[44:47]
	v_mfma_f32_16x16x32_bf16 v[40:43], v[132:135], v[156:159], v[40:43]
	v_mfma_f32_16x16x32_bf16 v[28:31], v[124:127], v[164:167], v[28:31]
	v_mfma_f32_16x16x32_bf16 v[24:27], v[132:135], v[164:167], v[24:27]
	s_waitcnt lgkmcnt(0)
	v_mfma_f32_16x16x32_bf16 v[12:15], v[124:127], v[172:175], v[12:15]
	v_mfma_f32_16x16x32_bf16 v[8:11], v[132:135], v[172:175], v[8:11]
	s_barrier
	s_add_u32 s48, s64, 0x84000
	s_addc_u32 s49, s65, 0
	s_mov_b32 m0, s43
	s_nop 0
	global_load_lds_dwordx4 v188, s[48:49]
	s_add_u32 s48, s64, 0x86000
	s_addc_u32 s49, s65, 0
	s_mov_b32 m0, s66
	s_nop 0
	global_load_lds_dwordx4 v188, s[48:49]
	s_waitcnt vmcnt(10)
	s_barrier
	v_mfma_f32_16x16x32_bf16 v[52:55], v[176:179], v[136:139], v[52:55]
	v_mfma_f32_16x16x32_bf16 v[48:51], v[184:187], v[136:139], v[48:51]
	v_mfma_f32_16x16x32_bf16 v[36:39], v[176:179], v[152:155], v[36:39]
	v_mfma_f32_16x16x32_bf16 v[32:35], v[184:187], v[152:155], v[32:35]
	v_mfma_f32_16x16x32_bf16 v[20:23], v[176:179], v[160:163], v[20:23]
	v_mfma_f32_16x16x32_bf16 v[16:19], v[184:187], v[160:163], v[16:19]
	v_mfma_f32_16x16x32_bf16 v[4:7], v[176:179], v[168:171], v[4:7]
	v_mfma_f32_16x16x32_bf16 v[0:3], v[184:187], v[168:171], v[0:3]
	v_mfma_f32_16x16x32_bf16 v[52:55], v[180:183], v[140:143], v[52:55]
	v_mfma_f32_16x16x32_bf16 v[48:51], v[200:203], v[140:143], v[48:51]
	v_mfma_f32_16x16x32_bf16 v[36:39], v[180:183], v[156:159], v[36:39]
	v_mfma_f32_16x16x32_bf16 v[32:35], v[200:203], v[156:159], v[32:35]
	v_mfma_f32_16x16x32_bf16 v[20:23], v[180:183], v[164:167], v[20:23]
	v_mfma_f32_16x16x32_bf16 v[16:19], v[200:203], v[164:167], v[16:19]
	v_mfma_f32_16x16x32_bf16 v[4:7], v[180:183], v[172:175], v[4:7]
	v_mfma_f32_16x16x32_bf16 v[0:3], v[200:203], v[172:175], v[0:3]
	s_add_i32 s71, s71, 2
	s_add_u32 s69, s69, 0x8000
	s_addc_u32 s70, s70, 0
	s_cmp_gt_u32 s71, 29
	s_mov_b64 s[60:61], s[62:63]
	s_barrier

; #define PG8_STAGE(bufoff, gbase, hoff, imm) do { _Pragma("unroll") for (int _i = 0; _i < 2; ++_i) { \
;         asm volatile("s_mov_b32 m0, %0\n\ts_nop 0\n\tglobal_load_lds_dwordx4 %1, %2" \
;             :: "s"(lds0 + (unsigned)((bufoff) + _i * 8192)), "v"(voff0), "s"((const char*)(gbase) + (size_t)(hoff) + (size_t)(_i * 8192)) : "memory"); } } while (0)
; #define PG8_LDA(dst, b, h) do { _Pragma("unroll") for (int m = 0; m < 4; ++m) _Pragma("unroll") for (int k = 0; k < 2; ++k) dst[m][k] = *(const LAS bf16x8*)(lds + PG8_SA(b, h) + aoff + m * 2048 + k * 1024); } while (0)
; #define PG8_LDB(dst, b, h) do { _Pragma("unroll") for (int n = 0; n < 2; ++n) _Pragma("unroll") for (int k = 0; k < 2; ++k) dst[n][k] = *(const LAS bf16x8*)(lds + PG8_SB(b, h) + boff + n * 2048 + k * 1024); } while (0)
; #define PG8_WAIT_V(n) asm volatile("s_waitcnt vmcnt(" #n ")" ::: "memory")
; #define PG8_WAIT_L(n) asm volatile("s_waitcnt lgkmcnt(" #n ")" ::: "memory")
; #define PG8_BAR __builtin_amdgcn_s_barrier()
; template <class Epi>
; __device__ __forceinline__ void gemm_phase(LAS unsigned char* lds, const Gemm g, const StaticOrder& S, const Epi& E) {
;     ...
;         const bool has_next = S.next(ui + 1, nxt);
;         const char* nA = has_next ? (const char*)g.A + (size_t)nxt.pm * tstepA + (size_t)(nxt.pn >> g.gshift) * g.gstride : cA;
;         const char* nB = has_next ? (const char*)g.Bt + (size_t)nxt.pn * tstepB : cB;
;         for (int t = 0; t < nt; t += 2) {
;             const bool last = (t == nt - 2);
;             if (last) E.pre(cur, wid, lane, (unsigned)(size_t)(lds + STAGE_BYTES));
;             const char* aT = cA + (size_t)t * KS;
;             const char* a2 = last ? nA : aT + 2 * KS; const char* b2 = last ? nB : cB + (size_t)(t + 2) * KS;
;             PG8_LDB(B0, 0, 0); PG8_SCHED; PG8_LDA(At, 0, 0); PG8_STAGE(PG8_SA(1, 1), aT + KS, hA, 0);
;             PG8_WAIT_L(8); PG8_BAR; PG8_WAIT_L(0); PG8_MMA(0, 0, At, B0); PG8_BAR; PG8_SCHED;
;             PG8_LDB(B1, 0, 1); PG8_STAGE(PG8_SB(0, 0), b2, 0, 0);
;             PG8_BAR; PG8_WAIT_L(0); PG8_MMA(0, 1, At, B1); PG8_BAR;
;             PG8_LDA(At, 0, 1); PG8_STAGE(PG8_SA(0, 0), a2, 0, 0);
;             PG8_BAR; PG8_WAIT_L(0); PG8_MMA(1, 0, At, B0); PG8_BAR; PG8_SCHED;
;             PG8_STAGE(PG8_SB(0, 1), b2, hB, 0);
;             PG8_WAIT_V(6); PG8_BAR; PG8_MMA(1, 1, At, B1); PG8_BAR;
.LBB0_737:
	s_ashr_i32 s71, s70, 31
	v_cmp_lt_i64_e32 vcc, s[8:9], v[198:199]
	s_lshl_b64 s[8:9], s[70:71], 20
	s_add_u32 s72, s26, s8
	s_addc_u32 s73, s27, s9
	s_and_b64 s[8:9], vcc, exec
	s_cselect_b32 s50, s73, s77
	s_cselect_b32 s51, s72, s76
	s_ashr_i32 s69, s68, 31
	s_lshl_b64 s[8:9], s[68:69], 20
	s_add_u32 s74, s84, s8
	s_addc_u32 s75, s85, s9
	s_and_b64 s[8:9], vcc, exec
	s_cselect_b32 s69, s75, s79
	s_cselect_b32 s0, s74, s78
	s_lshl_b32 s8, s1, 7
	s_ashr_i32 s9, s8, 31
	s_lshl_b64 s[10:11], s[8:9], 2
	s_add_u32 s10, s96, s10
	s_addc_u32 s11, s30, s11
	s_add_u32 s1, s78, 0x8000
	s_addc_u32 s9, s79, 0
	s_mov_b32 s71, -2
	v_add_u32_e32 v140, 0x10000, v177
	ds_read_b128 v[128:131], v140
	ds_read_b128 v[132:135], v140 offset:1024
	ds_read_b128 v[136:139], v140 offset:2048
	ds_read_b128 v[140:143], v140 offset:3072
	s_mov_b64 s[82:83], 0
	s_add_u32 s78, s76, 0x8000
	s_addc_u32 s79, s77, 0
	s_and_b64 s[48:49], s[82:83], exec
	s_cselect_b32 s81, s50, s79
	s_cselect_b32 s80, s51, s78
	ds_read_b128 v[144:147], v178
	ds_read_b128 v[148:151], v178 offset:1024
	ds_read_b128 v[184:187], v178 offset:2048
	ds_read_b128 v[200:203], v178 offset:3072
	ds_read_b128 v[204:207], v178 offset:4096
	ds_read_b128 v[208:211], v178 offset:5120
	ds_read_b128 v[212:215], v178 offset:6144
	ds_read_b128 v[236:239], v178 offset:7168
	s_waitcnt lgkmcnt(8)
	s_waitcnt vmcnt(10)
	s_barrier
	s_waitcnt lgkmcnt(7)
	v_mfma_f32_16x16x32_bf16 v[116:119], v[128:131], v[144:147], 0
	v_mfma_f32_16x16x32_bf16 v[80:83], v[136:139], v[144:147], 0
	s_waitcnt lgkmcnt(5)
	v_mfma_f32_16x16x32_bf16 v[88:91], v[128:131], v[184:187], 0
	v_mfma_f32_16x16x32_bf16 v[84:87], v[136:139], v[184:187], 0
	s_waitcnt lgkmcnt(3)
	v_mfma_f32_16x16x32_bf16 v[120:123], v[128:131], v[204:207], 0
	v_mfma_f32_16x16x32_bf16 v[92:95], v[136:139], v[204:207], 0
	s_waitcnt lgkmcnt(1)
	v_mfma_f32_16x16x32_bf16 v[124:127], v[128:131], v[212:215], 0
	v_mfma_f32_16x16x32_bf16 v[96:99], v[136:139], v[212:215], 0
	v_mfma_f32_16x16x32_bf16 v[116:119], v[132:135], v[148:151], v[116:119]
	v_mfma_f32_16x16x32_bf16 v[80:83], v[140:143], v[148:151], v[80:83]
	v_mfma_f32_16x16x32_bf16 v[88:91], v[132:135], v[200:203], v[88:91]
	v_mfma_f32_16x16x32_bf16 v[84:87], v[140:143], v[200:203], v[84:87]
	v_mfma_f32_16x16x32_bf16 v[120:123], v[132:135], v[208:211], v[120:123]
	v_mfma_f32_16x16x32_bf16 v[92:95], v[140:143], v[208:211], v[92:95]
	s_waitcnt lgkmcnt(0)
	v_mfma_f32_16x16x32_bf16 v[124:127], v[132:135], v[236:239], v[124:127]
	v_mfma_f32_16x16x32_bf16 v[96:99], v[140:143], v[236:239], v[96:99]
	s_barrier
	v_add_u32_e32 v188, 0x14000, v177
	ds_read_b128 v[240:243], v188
	ds_read_b128 v[244:247], v188 offset:1024
	ds_read_b128 v[248:251], v188 offset:2048
	ds_read_b128 v[230:233], v188 offset:3072
	s_and_b64 s[48:49], s[82:83], exec
	s_cselect_b32 s76, s0, s1
	s_cselect_b32 s77, s69, s9
	s_mov_b32 m0, s28
	s_nop 0
	global_load_lds_dwordx4 v152, s[76:77]
	s_add_u32 s48, s76, 0x2000
	s_addc_u32 s49, s77, 0
	s_mov_b32 m0, s29
	s_nop 0
	global_load_lds_dwordx4 v152, s[48:49]
	s_waitcnt vmcnt(10)
	s_barrier
	s_waitcnt lgkmcnt(3)
	v_mfma_f32_16x16x32_bf16 v[48:51], v[240:243], v[144:147], 0
	s_waitcnt lgkmcnt(1)
	v_mfma_f32_16x16x32_bf16 v[16:19], v[248:251], v[144:147], 0
	v_mfma_f32_16x16x32_bf16 v[52:55], v[240:243], v[184:187], 0
	v_mfma_f32_16x16x32_bf16 v[20:23], v[248:251], v[184:187], 0
	v_mfma_f32_16x16x32_bf16 v[56:59], v[240:243], v[204:207], 0
	v_mfma_f32_16x16x32_bf16 v[24:27], v[248:251], v[204:207], 0
	v_mfma_f32_16x16x32_bf16 v[60:63], v[240:243], v[212:215], 0
	v_mfma_f32_16x16x32_bf16 v[28:31], v[248:251], v[212:215], 0
	v_mfma_f32_16x16x32_bf16 v[48:51], v[244:247], v[148:151], v[48:51]
	s_waitcnt lgkmcnt(0)
	v_mfma_f32_16x16x32_bf16 v[16:19], v[230:233], v[148:151], v[16:19]
	v_mfma_f32_16x16x32_bf16 v[52:55], v[244:247], v[200:203], v[52:55]
	v_mfma_f32_16x16x32_bf16 v[20:23], v[230:233], v[200:203], v[20:23]
	v_mfma_f32_16x16x32_bf16 v[56:59], v[244:247], v[208:211], v[56:59]
	v_mfma_f32_16x16x32_bf16 v[24:27], v[230:233], v[208:211], v[24:27]
	v_mfma_f32_16x16x32_bf16 v[60:63], v[244:247], v[236:239], v[60:63]
	v_mfma_f32_16x16x32_bf16 v[28:31], v[230:233], v[236:239], v[28:31]
	s_barrier
	ds_read_b128 v[144:147], v178 offset:16384
	ds_read_b128 v[148:151], v178 offset:17408
	ds_read_b128 v[184:187], v178 offset:18432
	ds_read_b128 v[200:203], v178 offset:19456
	ds_read_b128 v[204:207], v178 offset:20480
	ds_read_b128 v[208:211], v178 offset:21504
	ds_read_b128 v[212:215], v178 offset:22528
	ds_read_b128 v[236:239], v178 offset:23552
	s_mov_b32 m0, s89
	s_nop 0
	global_load_lds_dwordx4 v152, s[80:81]
	s_add_u32 s48, s80, 0x2000
	s_addc_u32 s49, s81, 0
	s_mov_b32 m0, s40
	s_nop 0
	global_load_lds_dwordx4 v152, s[48:49]
	s_waitcnt vmcnt(10)
	s_barrier
	s_waitcnt lgkmcnt(7)
	v_mfma_f32_16x16x32_bf16 v[100:103], v[128:131], v[144:147], 0
	v_mfma_f32_16x16x32_bf16 v[64:67], v[136:139], v[144:147], 0
	s_waitcnt lgkmcnt(5)
	v_mfma_f32_16x16x32_bf16 v[104:107], v[128:131], v[184:187], 0
	v_mfma_f32_16x16x32_bf16 v[68:71], v[136:139], v[184:187], 0
	s_waitcnt lgkmcnt(3)
	v_mfma_f32_16x16x32_bf16 v[108:111], v[128:131], v[204:207], 0
	v_mfma_f32_16x16x32_bf16 v[72:75], v[136:139], v[204:207], 0
	s_waitcnt lgkmcnt(1)
	v_mfma_f32_16x16x32_bf16 v[112:115], v[128:131], v[212:215], 0
	v_mfma_f32_16x16x32_bf16 v[76:79], v[136:139], v[212:215], 0
	v_mfma_f32_16x16x32_bf16 v[100:103], v[132:135], v[148:151], v[100:103]
	v_mfma_f32_16x16x32_bf16 v[64:67], v[140:143], v[148:151], v[64:67]
	v_mfma_f32_16x16x32_bf16 v[104:107], v[132:135], v[200:203], v[104:107]
	v_mfma_f32_16x16x32_bf16 v[68:71], v[140:143], v[200:203], v[68:71]
	v_mfma_f32_16x16x32_bf16 v[108:111], v[132:135], v[208:211], v[108:111]
	v_mfma_f32_16x16x32_bf16 v[72:75], v[140:143], v[208:211], v[72:75]
	s_waitcnt lgkmcnt(0)
	v_mfma_f32_16x16x32_bf16 v[112:115], v[132:135], v[236:239], v[112:115]
	v_mfma_f32_16x16x32_bf16 v[76:79], v[140:143], v[236:239], v[76:79]
	s_barrier
; #define PG8_STAGE(bufoff, gbase, hoff, imm) do { _Pragma("unroll") for (int _i = 0; _i < 2; ++_i) { \
;         asm volatile("s_mov_b32 m0, %0\n\ts_nop 0\n\tglobal_load_lds_dwordx4 %1, %2" \
;             :: "s"(lds0 + (unsigned)((bufoff) + _i * 8192)), "v"(voff0), "s"((const char*)(gbase) + (size_t)(hoff) + (size_t)(_i * 8192)) : "memory"); } } while (0)
; #define PG8_LDA(dst, b, h) do { _Pragma("unroll") for (int m = 0; m < 4; ++m) _Pragma("unroll") for (int k = 0; k < 2; ++k) dst[m][k] = *(const LAS bf16x8*)(lds + PG8_SA(b, h) + aoff + m * 2048 + k * 1024); } while (0)
; #define PG8_LDB(dst, b, h) do { _Pragma("unroll") for (int n = 0; n < 2; ++n) _Pragma("unroll") for (int k = 0; k < 2; ++k) dst[n][k] = *(const LAS bf16x8*)(lds + PG8_SB(b, h) + boff + n * 2048 + k * 1024); } while (0)
; #define PG8_MMA(ai, bj, At, Bt) do { __builtin_amdgcn_s_setprio(1); _Pragma("unroll") for (int m = 0; m < 4; ++m) _Pragma("unroll") for (int n = 0; n < 2; ++n) _Pragma("unroll") for (int k = 0; k < 2; ++k) \
;         acc[ai][bj][m][n] = __builtin_amdgcn_mfma_f32_16x16x32_bf16(Bt[n][k], At[m][k], acc[ai][bj][m][n], 0, 0, 0); __builtin_amdgcn_s_setprio(0); } while (0)
; #define PG8_WAIT_V(n) asm volatile("s_waitcnt vmcnt(" #n ")" ::: "memory")
; #define PG8_WAIT_L(n) asm volatile("s_waitcnt lgkmcnt(" #n ")" ::: "memory")
; #define PG8_BAR __builtin_amdgcn_s_barrier()
; #define PG8_SCHED __builtin_amdgcn_sched_barrier(0)
; template <class Epi>
; __device__ __forceinline__ void gemm_phase(LAS unsigned char* lds, const Gemm g, const StaticOrder& S, const Epi& E) {
;     ...
;             PG8_STAGE(PG8_SB(0, 1), b2, hB, 0);
;             PG8_WAIT_V(6); PG8_BAR; PG8_MMA(1, 1, At, B1); PG8_BAR;
;             PG8_LDB(B0, 1, 0); PG8_SCHED; PG8_LDA(At, 1, 0); PG8_STAGE(PG8_SA(0, 1), a2, hA, 0);
;             PG8_WAIT_L(8); PG8_BAR; PG8_WAIT_L(0); PG8_MMA(0, 0, At, B0); PG8_BAR; PG8_SCHED;
;             PG8_LDB(B1, 1, 1); PG8_STAGE(PG8_SB(1, 0), b2 + KS, 0, 0);
;             PG8_BAR; PG8_WAIT_L(0); PG8_MMA(0, 1, At, B1); PG8_BAR;
	v_add_u32_e32 v140, 0x18000, v177
	ds_read_b128 v[128:131], v140
	ds_read_b128 v[132:135], v140 offset:1024
	ds_read_b128 v[136:139], v140 offset:2048
	ds_read_b128 v[140:143], v140 offset:3072
	s_add_u32 s48, s76, 0x80000
	s_addc_u32 s49, s77, 0
	s_mov_b32 m0, s41
	s_nop 0
	global_load_lds_dwordx4 v152, s[48:49]
	s_add_u32 s48, s76, 0x82000
	s_addc_u32 s49, s77, 0
	s_mov_b32 m0, s42
	s_nop 0
	global_load_lds_dwordx4 v152, s[48:49]
	s_add_u32 s48, s80, 0x80000
	s_addc_u32 s49, s81, 0
	s_mov_b32 m0, s43
	s_nop 0
	global_load_lds_dwordx4 v152, s[48:49]
	s_add_u32 s48, s80, 0x82000
	s_addc_u32 s49, s81, 0
	s_mov_b32 m0, s92
	s_nop 0
	global_load_lds_dwordx4 v152, s[48:49]
	s_waitcnt vmcnt(12)
	s_barrier
	v_mfma_f32_16x16x32_bf16 v[32:35], v[240:243], v[144:147], 0
	v_mfma_f32_16x16x32_bf16 v[0:3], v[248:251], v[144:147], 0
	v_mfma_f32_16x16x32_bf16 v[36:39], v[240:243], v[184:187], 0
	v_mfma_f32_16x16x32_bf16 v[4:7], v[248:251], v[184:187], 0
	v_mfma_f32_16x16x32_bf16 v[40:43], v[240:243], v[204:207], 0
	v_mfma_f32_16x16x32_bf16 v[8:11], v[248:251], v[204:207], 0
	v_mfma_f32_16x16x32_bf16 v[44:47], v[240:243], v[212:215], 0
	v_mfma_f32_16x16x32_bf16 v[12:15], v[248:251], v[212:215], 0
	v_mfma_f32_16x16x32_bf16 v[32:35], v[244:247], v[148:151], v[32:35]
	v_mfma_f32_16x16x32_bf16 v[0:3], v[230:233], v[148:151], v[0:3]
	v_mfma_f32_16x16x32_bf16 v[36:39], v[244:247], v[200:203], v[36:39]
	v_mfma_f32_16x16x32_bf16 v[4:7], v[230:233], v[200:203], v[4:7]
	v_mfma_f32_16x16x32_bf16 v[40:43], v[244:247], v[208:211], v[40:43]
	v_mfma_f32_16x16x32_bf16 v[8:11], v[230:233], v[208:211], v[8:11]
	v_mfma_f32_16x16x32_bf16 v[44:47], v[244:247], v[236:239], v[44:47]
	v_mfma_f32_16x16x32_bf16 v[12:15], v[230:233], v[236:239], v[12:15]
	s_barrier
	ds_read_b128 v[144:147], v178 offset:32768
	ds_read_b128 v[148:151], v178 offset:33792
	ds_read_b128 v[184:187], v178 offset:34816
	ds_read_b128 v[200:203], v178 offset:35840
	ds_read_b128 v[204:207], v178 offset:36864
	ds_read_b128 v[208:211], v178 offset:37888
	ds_read_b128 v[212:215], v178 offset:38912
	ds_read_b128 v[230:233], v178 offset:39936
	s_waitcnt lgkmcnt(8)
	s_waitcnt vmcnt(10)
	s_barrier
	s_waitcnt lgkmcnt(7)
	v_mfma_f32_16x16x32_bf16 v[116:119], v[128:131], v[144:147], v[116:119]
	v_mfma_f32_16x16x32_bf16 v[80:83], v[136:139], v[144:147], v[80:83]
	s_waitcnt lgkmcnt(5)
	v_mfma_f32_16x16x32_bf16 v[88:91], v[128:131], v[184:187], v[88:91]
	v_mfma_f32_16x16x32_bf16 v[84:87], v[136:139], v[184:187], v[84:87]
	s_waitcnt lgkmcnt(3)
	v_mfma_f32_16x16x32_bf16 v[120:123], v[128:131], v[204:207], v[120:123]
	v_mfma_f32_16x16x32_bf16 v[92:95], v[136:139], v[204:207], v[92:95]
	s_waitcnt lgkmcnt(1)
	v_mfma_f32_16x16x32_bf16 v[124:127], v[128:131], v[212:215], v[124:127]
	v_mfma_f32_16x16x32_bf16 v[96:99], v[136:139], v[212:215], v[96:99]
	v_mfma_f32_16x16x32_bf16 v[116:119], v[132:135], v[148:151], v[116:119]
	v_mfma_f32_16x16x32_bf16 v[80:83], v[140:143], v[148:151], v[80:83]
	v_mfma_f32_16x16x32_bf16 v[88:91], v[132:135], v[200:203], v[88:91]
	v_mfma_f32_16x16x32_bf16 v[84:87], v[140:143], v[200:203], v[84:87]
	v_mfma_f32_16x16x32_bf16 v[120:123], v[132:135], v[208:211], v[120:123]
	v_mfma_f32_16x16x32_bf16 v[92:95], v[140:143], v[208:211], v[92:95]
	s_waitcnt lgkmcnt(0)
	v_mfma_f32_16x16x32_bf16 v[124:127], v[132:135], v[230:233], v[124:127]
	v_mfma_f32_16x16x32_bf16 v[96:99], v[140:143], v[230:233], v[96:99]
	s_barrier
	v_add_u32_e32 v188, 0x1c000, v177
	ds_read_b128 v[236:239], v188
	ds_read_b128 v[240:243], v188 offset:1024
	ds_read_b128 v[244:247], v188 offset:2048
	ds_read_b128 v[248:251], v188 offset:3072
	s_add_u32 s48, s76, 0x4000
	s_addc_u32 s49, s77, 0
	s_mov_b32 m0, s16
	s_nop 0
	global_load_lds_dwordx4 v152, s[48:49]
	s_add_u32 s48, s76, 0x6000
	s_addc_u32 s49, s77, 0
	s_mov_b32 m0, s17
	s_nop 0
	global_load_lds_dwordx4 v152, s[48:49]
	s_waitcnt vmcnt(10)
	s_barrier
; #define PG8_STAGE(bufoff, gbase, hoff, imm) do { _Pragma("unroll") for (int _i = 0; _i < 2; ++_i) { \
;         asm volatile("s_mov_b32 m0, %0\n\ts_nop 0\n\tglobal_load_lds_dwordx4 %1, %2" \
;             :: "s"(lds0 + (unsigned)((bufoff) + _i * 8192)), "v"(voff0), "s"((const char*)(gbase) + (size_t)(hoff) + (size_t)(_i * 8192)) : "memory"); } } while (0)
; #define PG8_LDA(dst, b, h) do { _Pragma("unroll") for (int m = 0; m < 4; ++m) _Pragma("unroll") for (int k = 0; k < 2; ++k) dst[m][k] = *(const LAS bf16x8*)(lds + PG8_SA(b, h) + aoff + m * 2048 + k * 1024); } while (0)
; #define PG8_LDB(dst, b, h) do { _Pragma("unroll") for (int n = 0; n < 2; ++n) _Pragma("unroll") for (int k = 0; k < 2; ++k) dst[n][k] = *(const LAS bf16x8*)(lds + PG8_SB(b, h) + boff + n * 2048 + k * 1024); } while (0)
; #define PG8_MMA(ai, bj, At, Bt) do { __builtin_amdgcn_s_setprio(1); _Pragma("unroll") for (int m = 0; m < 4; ++m) _Pragma("unroll") for (int n = 0; n < 2; ++n) _Pragma("unroll") for (int k = 0; k < 2; ++k) \
;         acc[ai][bj][m][n] = __builtin_amdgcn_mfma_f32_16x16x32_bf16(Bt[n][k], At[m][k], acc[ai][bj][m][n], 0, 0, 0); __builtin_amdgcn_s_setprio(0); } while (0)
; #define PG8_WAIT_V(n) asm volatile("s_waitcnt vmcnt(" #n ")" ::: "memory")
; #define PG8_WAIT_L(n) asm volatile("s_waitcnt lgkmcnt(" #n ")" ::: "memory")
; #define PG8_BAR __builtin_amdgcn_s_barrier()
; #define PG8_SCHED __builtin_amdgcn_sched_barrier(0)
; template <class Epi>
; __device__ __forceinline__ void gemm_phase(LAS unsigned char* lds, const Gemm g, const StaticOrder& S, const Epi& E) {
;     ...
;             PG8_LDB(B1, 1, 1); PG8_STAGE(PG8_SB(1, 0), b2 + KS, 0, 0);
;             PG8_BAR; PG8_WAIT_L(0); PG8_MMA(0, 1, At, B1); PG8_BAR;
;             PG8_LDA(At, 1, 1); PG8_STAGE(PG8_SA(1, 0), a2 + KS, 0, 0);
;             PG8_BAR; PG8_WAIT_L(0); PG8_MMA(1, 0, At, B0); PG8_BAR; PG8_SCHED;
;             PG8_STAGE(PG8_SB(1, 1), b2 + KS, hB, 0);
;             PG8_WAIT_V(6); PG8_BAR; PG8_MMA(1, 1, At, B1); PG8_BAR;
	s_waitcnt lgkmcnt(3)
	v_mfma_f32_16x16x32_bf16 v[48:51], v[236:239], v[144:147], v[48:51]
	s_waitcnt lgkmcnt(1)
	v_mfma_f32_16x16x32_bf16 v[16:19], v[244:247], v[144:147], v[16:19]
	v_mfma_f32_16x16x32_bf16 v[52:55], v[236:239], v[184:187], v[52:55]
	v_mfma_f32_16x16x32_bf16 v[20:23], v[244:247], v[184:187], v[20:23]
	v_mfma_f32_16x16x32_bf16 v[56:59], v[236:239], v[204:207], v[56:59]
	v_mfma_f32_16x16x32_bf16 v[24:27], v[244:247], v[204:207], v[24:27]
	v_mfma_f32_16x16x32_bf16 v[60:63], v[236:239], v[212:215], v[60:63]
	v_mfma_f32_16x16x32_bf16 v[28:31], v[244:247], v[212:215], v[28:31]
	v_mfma_f32_16x16x32_bf16 v[48:51], v[240:243], v[148:151], v[48:51]
	s_waitcnt lgkmcnt(0)
	v_mfma_f32_16x16x32_bf16 v[16:19], v[248:251], v[148:151], v[16:19]
	v_mfma_f32_16x16x32_bf16 v[52:55], v[240:243], v[200:203], v[52:55]
	v_mfma_f32_16x16x32_bf16 v[20:23], v[248:251], v[200:203], v[20:23]
	v_mfma_f32_16x16x32_bf16 v[56:59], v[240:243], v[208:211], v[56:59]
	v_mfma_f32_16x16x32_bf16 v[24:27], v[248:251], v[208:211], v[24:27]
	v_mfma_f32_16x16x32_bf16 v[60:63], v[240:243], v[230:233], v[60:63]
	v_mfma_f32_16x16x32_bf16 v[28:31], v[248:251], v[230:233], v[28:31]
	s_barrier
	ds_read_b128 v[144:147], v178 offset:49152
	ds_read_b128 v[148:151], v178 offset:50176
	ds_read_b128 v[184:187], v178 offset:51200
	ds_read_b128 v[200:203], v178 offset:52224
	ds_read_b128 v[204:207], v178 offset:53248
	ds_read_b128 v[208:211], v178 offset:54272
	ds_read_b128 v[212:215], v178 offset:55296
	ds_read_b128 v[230:233], v178 offset:56320
	s_add_u32 s48, s80, 0x4000
	s_addc_u32 s49, s81, 0
	s_mov_b32 m0, s24
	s_nop 0
	global_load_lds_dwordx4 v152, s[48:49]
	s_add_u32 s48, s80, 0x6000
	s_addc_u32 s49, s81, 0
	s_mov_b32 m0, s37
	s_nop 0
	global_load_lds_dwordx4 v152, s[48:49]
	s_waitcnt vmcnt(10)
	s_barrier
	s_waitcnt lgkmcnt(7)
	v_mfma_f32_16x16x32_bf16 v[100:103], v[128:131], v[144:147], v[100:103]
	v_mfma_f32_16x16x32_bf16 v[64:67], v[136:139], v[144:147], v[64:67]
	s_waitcnt lgkmcnt(5)
	v_mfma_f32_16x16x32_bf16 v[104:107], v[128:131], v[184:187], v[104:107]
	v_mfma_f32_16x16x32_bf16 v[68:71], v[136:139], v[184:187], v[68:71]
	s_waitcnt lgkmcnt(3)
	v_mfma_f32_16x16x32_bf16 v[108:111], v[128:131], v[204:207], v[108:111]
	v_mfma_f32_16x16x32_bf16 v[72:75], v[136:139], v[204:207], v[72:75]
	s_waitcnt lgkmcnt(1)
	v_mfma_f32_16x16x32_bf16 v[112:115], v[128:131], v[212:215], v[112:115]
	v_mfma_f32_16x16x32_bf16 v[76:79], v[136:139], v[212:215], v[76:79]
	v_mfma_f32_16x16x32_bf16 v[100:103], v[132:135], v[148:151], v[100:103]
	v_mfma_f32_16x16x32_bf16 v[64:67], v[140:143], v[148:151], v[64:67]
	v_mfma_f32_16x16x32_bf16 v[104:107], v[132:135], v[200:203], v[104:107]
	v_mfma_f32_16x16x32_bf16 v[68:71], v[140:143], v[200:203], v[68:71]
	v_mfma_f32_16x16x32_bf16 v[108:111], v[132:135], v[208:211], v[108:111]
	v_mfma_f32_16x16x32_bf16 v[72:75], v[140:143], v[208:211], v[72:75]
	s_waitcnt lgkmcnt(0)
	v_mfma_f32_16x16x32_bf16 v[112:115], v[132:135], v[230:233], v[112:115]
	v_mfma_f32_16x16x32_bf16 v[76:79], v[140:143], v[230:233], v[76:79]
	s_barrier
	v_add_u32_e32 v140, 0x10000, v177
	ds_read_b128 v[128:131], v140
	ds_read_b128 v[132:135], v140 offset:1024
	ds_read_b128 v[136:139], v140 offset:2048
	ds_read_b128 v[140:143], v140 offset:3072
	s_add_u32 s48, s76, 0x84000
	s_addc_u32 s49, s77, 0
	s_mov_b32 m0, s97
	s_nop 0
	global_load_lds_dwordx4 v152, s[48:49]
	s_add_u32 s48, s76, 0x86000
	s_addc_u32 s49, s77, 0
	s_mov_b32 m0, s38
	s_nop 0
	global_load_lds_dwordx4 v152, s[48:49]
	s_add_u32 s48, s80, 0x84000
	s_addc_u32 s49, s81, 0
	s_mov_b32 m0, s34
	s_nop 0
	global_load_lds_dwordx4 v152, s[48:49]
	s_add_u32 s48, s80, 0x86000
	s_addc_u32 s49, s81, 0
	s_mov_b32 m0, s25
	s_nop 0
	global_load_lds_dwordx4 v152, s[48:49]
	s_waitcnt vmcnt(12)
	s_barrier
	v_mfma_f32_16x16x32_bf16 v[32:35], v[236:239], v[144:147], v[32:35]
	v_mfma_f32_16x16x32_bf16 v[0:3], v[244:247], v[144:147], v[0:3]
	v_mfma_f32_16x16x32_bf16 v[36:39], v[236:239], v[184:187], v[36:39]
	v_mfma_f32_16x16x32_bf16 v[4:7], v[244:247], v[184:187], v[4:7]
	v_mfma_f32_16x16x32_bf16 v[40:43], v[236:239], v[204:207], v[40:43]
	v_mfma_f32_16x16x32_bf16 v[8:11], v[244:247], v[204:207], v[8:11]
	v_mfma_f32_16x16x32_bf16 v[44:47], v[236:239], v[212:215], v[44:47]
	v_mfma_f32_16x16x32_bf16 v[12:15], v[244:247], v[212:215], v[12:15]
	v_mfma_f32_16x16x32_bf16 v[32:35], v[240:243], v[148:151], v[32:35]
	v_mfma_f32_16x16x32_bf16 v[0:3], v[248:251], v[148:151], v[0:3]
	v_mfma_f32_16x16x32_bf16 v[36:39], v[240:243], v[200:203], v[36:39]
	v_mfma_f32_16x16x32_bf16 v[4:7], v[248:251], v[200:203], v[4:7]
	v_mfma_f32_16x16x32_bf16 v[40:43], v[240:243], v[208:211], v[40:43]
	v_mfma_f32_16x16x32_bf16 v[8:11], v[248:251], v[208:211], v[8:11]
	v_mfma_f32_16x16x32_bf16 v[44:47], v[240:243], v[230:233], v[44:47]
	v_mfma_f32_16x16x32_bf16 v[12:15], v[248:251], v[230:233], v[12:15]
	s_add_i32 s71, s71, 2
	s_add_u32 s1, s1, 0x8000
	s_addc_u32 s9, s9, 0
	s_cmp_gt_u32 s71, 29
	s_mov_b64 s[76:77], s[78:79]
	s_barrier
	s_branch .LBB0_739

; #define PG8_STAGE(bufoff, gbase, hoff, imm) do { _Pragma("unroll") for (int _i = 0; _i < 2; ++_i) { \
;         asm volatile("s_mov_b32 m0, %0\n\ts_nop 0\n\tglobal_load_lds_dwordx4 %1, %2" \
;             :: "s"(lds0 + (unsigned)((bufoff) + _i * 8192)), "v"(voff0), "s"((const char*)(gbase) + (size_t)(hoff) + (size_t)(_i * 8192)) : "memory"); } } while (0)
; #define PG8_LDA(dst, b, h) do { _Pragma("unroll") for (int m = 0; m < 4; ++m) _Pragma("unroll") for (int k = 0; k < 2; ++k) dst[m][k] = *(const LAS bf16x8*)(lds + PG8_SA(b, h) + aoff + m * 2048 + k * 1024); } while (0)
; #define PG8_LDB(dst, b, h) do { _Pragma("unroll") for (int n = 0; n < 2; ++n) _Pragma("unroll") for (int k = 0; k < 2; ++k) dst[n][k] = *(const LAS bf16x8*)(lds + PG8_SB(b, h) + boff + n * 2048 + k * 1024); } while (0)
; #define PG8_MMA(ai, bj, At, Bt) do { __builtin_amdgcn_s_setprio(1); _Pragma("unroll") for (int m = 0; m < 4; ++m) _Pragma("unroll") for (int n = 0; n < 2; ++n) _Pragma("unroll") for (int k = 0; k < 2; ++k) \
;         acc[ai][bj][m][n] = __builtin_amdgcn_mfma_f32_16x16x32_bf16(Bt[n][k], At[m][k], acc[ai][bj][m][n], 0, 0, 0); __builtin_amdgcn_s_setprio(0); } while (0)
; #define PG8_WAIT_L(n) asm volatile("s_waitcnt lgkmcnt(" #n ")" ::: "memory")
; #define PG8_BAR __builtin_amdgcn_s_barrier()
; #define PG8_SCHED __builtin_amdgcn_sched_barrier(0)
; template <class Epi>
; __device__ __forceinline__ void gemm_phase(LAS unsigned char* lds, const Gemm g, const StaticOrder& S, const Epi& E) {
;     ...
;         for (int t = 0; t < nt; t += 2) {
;             const bool last = (t == nt - 2);
;             if (last) E.pre(cur, wid, lane, (unsigned)(size_t)(lds + STAGE_BYTES));
;             const char* aT = cA + (size_t)t * KS;
;             const char* a2 = last ? nA : aT + 2 * KS; const char* b2 = last ? nB : cB + (size_t)(t + 2) * KS;
;             PG8_LDB(B0, 0, 0); PG8_SCHED; PG8_LDA(At, 0, 0); PG8_STAGE(PG8_SA(1, 1), aT + KS, hA, 0);
;             PG8_WAIT_L(8); PG8_BAR; PG8_WAIT_L(0); PG8_MMA(0, 0, At, B0); PG8_BAR; PG8_SCHED;
;             PG8_LDB(B1, 0, 1); PG8_STAGE(PG8_SB(0, 0), b2, 0, 0);
;             PG8_BAR; PG8_WAIT_L(0); PG8_MMA(0, 1, At, B1); PG8_BAR;
;             PG8_LDA(At, 0, 1); PG8_STAGE(PG8_SA(0, 0), a2, 0, 0);
;             PG8_BAR; PG8_WAIT_L(0); PG8_MMA(1, 0, At, B0); PG8_BAR; PG8_SCHED;
.LBB0_859:
	s_add_u32 s0, s58, 0x8000
	s_addc_u32 s1, s59, 0
	s_mov_b32 s69, -2
	s_waitcnt vmcnt(16)
	s_add_u32 s58, s56, 0x8000
	v_add_u32_e32 v132, 0x10000, v236
	s_addc_u32 s59, s57, 0
	ds_read_b128 v[120:123], v132
	ds_read_b128 v[124:127], v132 offset:1024
	ds_read_b128 v[128:131], v132 offset:2048
	ds_read_b128 v[132:135], v132 offset:3072
	s_add_u32 s48, s56, 0x164000
	s_addc_u32 s49, s57, 0
	s_add_u32 s60, s56, 0x166000
	s_addc_u32 s61, s57, 0
	s_cmpk_eq_i32 s69, 0x54
	s_cselect_b32 s57, s7, s59
	s_cselect_b32 s56, s6, s58
	ds_read_b128 v[136:139], v237
	ds_read_b128 v[140:143], v237 offset:1024
	ds_read_b128 v[152:155], v237 offset:2048
	ds_read_b128 v[156:159], v237 offset:3072
	ds_read_b128 v[160:163], v237 offset:4096
	ds_read_b128 v[164:167], v237 offset:5120
	ds_read_b128 v[168:171], v237 offset:6144
	ds_read_b128 v[172:175], v237 offset:7168
	s_mov_b32 m0, s65
	s_nop 0
	global_load_lds_dwordx4 v188, s[48:49]
	s_mov_b32 m0, s66
	s_nop 0
	global_load_lds_dwordx4 v188, s[60:61]
	s_waitcnt lgkmcnt(8)
	s_waitcnt vmcnt(10)
	s_barrier
	s_waitcnt lgkmcnt(7)
	v_mfma_f32_16x16x32_bf16 v[148:151], v[120:123], v[136:139], 0
	v_mfma_f32_16x16x32_bf16 v[144:147], v[128:131], v[136:139], 0
	s_waitcnt lgkmcnt(5)
	v_mfma_f32_16x16x32_bf16 v[108:111], v[120:123], v[152:155], 0
	v_mfma_f32_16x16x32_bf16 v[104:107], v[128:131], v[152:155], 0
	s_waitcnt lgkmcnt(3)
	v_mfma_f32_16x16x32_bf16 v[92:95], v[120:123], v[160:163], 0
	v_mfma_f32_16x16x32_bf16 v[88:91], v[128:131], v[160:163], 0
	s_waitcnt lgkmcnt(1)
	v_mfma_f32_16x16x32_bf16 v[76:79], v[120:123], v[168:171], 0
	v_mfma_f32_16x16x32_bf16 v[72:75], v[128:131], v[168:171], 0
	v_mfma_f32_16x16x32_bf16 v[148:151], v[124:127], v[140:143], v[148:151]
	v_mfma_f32_16x16x32_bf16 v[144:147], v[132:135], v[140:143], v[144:147]
	v_mfma_f32_16x16x32_bf16 v[108:111], v[124:127], v[156:159], v[108:111]
	v_mfma_f32_16x16x32_bf16 v[104:107], v[132:135], v[156:159], v[104:107]
	v_mfma_f32_16x16x32_bf16 v[92:95], v[124:127], v[164:167], v[92:95]
	v_mfma_f32_16x16x32_bf16 v[88:91], v[132:135], v[164:167], v[88:91]
	s_waitcnt lgkmcnt(0)
	v_mfma_f32_16x16x32_bf16 v[76:79], v[124:127], v[172:175], v[76:79]
	v_mfma_f32_16x16x32_bf16 v[72:75], v[132:135], v[172:175], v[72:75]
	s_barrier
	v_add_u32_e32 v200, 0x14000, v236
	ds_read_b128 v[176:179], v200
	ds_read_b128 v[180:183], v200 offset:1024
	ds_read_b128 v[184:187], v200 offset:2048
	ds_read_b128 v[200:203], v200 offset:3072
	s_cselect_b32 s60, s8, s0
	s_cselect_b32 s61, s9, s1
	s_mov_b32 m0, s26
	s_nop 0
	global_load_lds_dwordx4 v188, s[60:61]
	s_add_u32 s48, s60, 0x2000
	s_addc_u32 s49, s61, 0
	s_mov_b32 m0, s27
	s_nop 0
	global_load_lds_dwordx4 v188, s[48:49]
	s_waitcnt vmcnt(10)
	s_barrier
	s_waitcnt lgkmcnt(3)
	v_mfma_f32_16x16x32_bf16 v[116:119], v[176:179], v[136:139], 0
	s_waitcnt lgkmcnt(1)
	v_mfma_f32_16x16x32_bf16 v[112:115], v[184:187], v[136:139], 0
	v_mfma_f32_16x16x32_bf16 v[100:103], v[176:179], v[152:155], 0
	v_mfma_f32_16x16x32_bf16 v[96:99], v[184:187], v[152:155], 0
	v_mfma_f32_16x16x32_bf16 v[84:87], v[176:179], v[160:163], 0
	v_mfma_f32_16x16x32_bf16 v[80:83], v[184:187], v[160:163], 0
	v_mfma_f32_16x16x32_bf16 v[68:71], v[176:179], v[168:171], 0
	v_mfma_f32_16x16x32_bf16 v[64:67], v[184:187], v[168:171], 0
	v_mfma_f32_16x16x32_bf16 v[116:119], v[180:183], v[140:143], v[116:119]
	s_waitcnt lgkmcnt(0)
	v_mfma_f32_16x16x32_bf16 v[112:115], v[200:203], v[140:143], v[112:115]
	v_mfma_f32_16x16x32_bf16 v[100:103], v[180:183], v[156:159], v[100:103]
	v_mfma_f32_16x16x32_bf16 v[96:99], v[200:203], v[156:159], v[96:99]
	v_mfma_f32_16x16x32_bf16 v[84:87], v[180:183], v[164:167], v[84:87]
	v_mfma_f32_16x16x32_bf16 v[80:83], v[200:203], v[164:167], v[80:83]
	v_mfma_f32_16x16x32_bf16 v[68:71], v[180:183], v[172:175], v[68:71]
	v_mfma_f32_16x16x32_bf16 v[64:67], v[200:203], v[172:175], v[64:67]
	s_barrier
	ds_read_b128 v[136:139], v237 offset:16384
	ds_read_b128 v[140:143], v237 offset:17408
	ds_read_b128 v[152:155], v237 offset:18432
	ds_read_b128 v[156:159], v237 offset:19456
	ds_read_b128 v[160:163], v237 offset:20480
	ds_read_b128 v[164:167], v237 offset:21504
	ds_read_b128 v[168:171], v237 offset:22528
	ds_read_b128 v[172:175], v237 offset:23552
	s_mov_b32 m0, s25
	s_nop 0
	global_load_lds_dwordx4 v188, s[56:57]
	s_add_u32 s48, s56, 0x2000
	s_addc_u32 s49, s57, 0
	s_mov_b32 m0, s28
	s_nop 0
	global_load_lds_dwordx4 v188, s[48:49]
	s_barrier
	s_waitcnt lgkmcnt(7)
	v_mfma_f32_16x16x32_bf16 v[60:63], v[120:123], v[136:139], 0
	v_mfma_f32_16x16x32_bf16 v[56:59], v[128:131], v[136:139], 0
	s_waitcnt lgkmcnt(5)
	v_mfma_f32_16x16x32_bf16 v[44:47], v[120:123], v[152:155], 0
	v_mfma_f32_16x16x32_bf16 v[40:43], v[128:131], v[152:155], 0
	s_waitcnt lgkmcnt(3)
	v_mfma_f32_16x16x32_bf16 v[28:31], v[120:123], v[160:163], 0
	v_mfma_f32_16x16x32_bf16 v[24:27], v[128:131], v[160:163], 0
	s_waitcnt lgkmcnt(1)
	v_mfma_f32_16x16x32_bf16 v[12:15], v[120:123], v[168:171], 0
	v_mfma_f32_16x16x32_bf16 v[8:11], v[128:131], v[168:171], 0
	v_mfma_f32_16x16x32_bf16 v[60:63], v[124:127], v[140:143], v[60:63]
	v_mfma_f32_16x16x32_bf16 v[56:59], v[132:135], v[140:143], v[56:59]
	v_mfma_f32_16x16x32_bf16 v[44:47], v[124:127], v[156:159], v[44:47]
	v_mfma_f32_16x16x32_bf16 v[40:43], v[132:135], v[156:159], v[40:43]
	v_mfma_f32_16x16x32_bf16 v[28:31], v[124:127], v[164:167], v[28:31]
	v_mfma_f32_16x16x32_bf16 v[24:27], v[132:135], v[164:167], v[24:27]
	s_waitcnt lgkmcnt(0)
	v_mfma_f32_16x16x32_bf16 v[12:15], v[124:127], v[172:175], v[12:15]
	v_mfma_f32_16x16x32_bf16 v[8:11], v[132:135], v[172:175], v[8:11]
	s_barrier
; #define PG8_STAGE(bufoff, gbase, hoff, imm) do { _Pragma("unroll") for (int _i = 0; _i < 2; ++_i) { \
;         asm volatile("s_mov_b32 m0, %0\n\ts_nop 0\n\tglobal_load_lds_dwordx4 %1, %2" \
;             :: "s"(lds0 + (unsigned)((bufoff) + _i * 8192)), "v"(voff0), "s"((const char*)(gbase) + (size_t)(hoff) + (size_t)(_i * 8192)) : "memory"); } } while (0)
; #define PG8_LDA(dst, b, h) do { _Pragma("unroll") for (int m = 0; m < 4; ++m) _Pragma("unroll") for (int k = 0; k < 2; ++k) dst[m][k] = *(const LAS bf16x8*)(lds + PG8_SA(b, h) + aoff + m * 2048 + k * 1024); } while (0)
; #define PG8_LDB(dst, b, h) do { _Pragma("unroll") for (int n = 0; n < 2; ++n) _Pragma("unroll") for (int k = 0; k < 2; ++k) dst[n][k] = *(const LAS bf16x8*)(lds + PG8_SB(b, h) + boff + n * 2048 + k * 1024); } while (0)
; #define PG8_MMA(ai, bj, At, Bt) do { __builtin_amdgcn_s_setprio(1); _Pragma("unroll") for (int m = 0; m < 4; ++m) _Pragma("unroll") for (int n = 0; n < 2; ++n) _Pragma("unroll") for (int k = 0; k < 2; ++k) \
;         acc[ai][bj][m][n] = __builtin_amdgcn_mfma_f32_16x16x32_bf16(Bt[n][k], At[m][k], acc[ai][bj][m][n], 0, 0, 0); __builtin_amdgcn_s_setprio(0); } while (0)
; #define PG8_WAIT_V(n) asm volatile("s_waitcnt vmcnt(" #n ")" ::: "memory")
; #define PG8_WAIT_L(n) asm volatile("s_waitcnt lgkmcnt(" #n ")" ::: "memory")
; #define PG8_BAR __builtin_amdgcn_s_barrier()
; #define PG8_SCHED __builtin_amdgcn_sched_barrier(0)
; template <class Epi>
; __device__ __forceinline__ void gemm_phase(LAS unsigned char* lds, const Gemm g, const StaticOrder& S, const Epi& E) {
;     ...
;             PG8_STAGE(PG8_SB(0, 1), b2, hB, 0);
;             PG8_WAIT_V(6); PG8_BAR; PG8_MMA(1, 1, At, B1); PG8_BAR;
;             PG8_LDB(B0, 1, 0); PG8_SCHED; PG8_LDA(At, 1, 0); PG8_STAGE(PG8_SA(0, 1), a2, hA, 0);
;             PG8_WAIT_L(8); PG8_BAR; PG8_WAIT_L(0); PG8_MMA(0, 0, At, B0); PG8_BAR; PG8_SCHED;
;             PG8_LDB(B1, 1, 1); PG8_STAGE(PG8_SB(1, 0), b2 + KS, 0, 0);
;             PG8_BAR; PG8_WAIT_L(0); PG8_MMA(0, 1, At, B1); PG8_BAR;
	s_add_u32 s48, s60, 0x160000
	s_addc_u32 s49, s61, 0
	s_mov_b32 m0, s29
	s_nop 0
	global_load_lds_dwordx4 v188, s[48:49]
	s_add_u32 s48, s60, 0x162000
	s_addc_u32 s49, s61, 0
	s_mov_b32 m0, s30
	s_nop 0
	global_load_lds_dwordx4 v188, s[48:49]
	s_waitcnt vmcnt(10)
	s_barrier
	v_mfma_f32_16x16x32_bf16 v[52:55], v[176:179], v[136:139], 0
	v_mfma_f32_16x16x32_bf16 v[48:51], v[184:187], v[136:139], 0
	v_mfma_f32_16x16x32_bf16 v[36:39], v[176:179], v[152:155], 0
	v_mfma_f32_16x16x32_bf16 v[32:35], v[184:187], v[152:155], 0
	v_mfma_f32_16x16x32_bf16 v[20:23], v[176:179], v[160:163], 0
	v_mfma_f32_16x16x32_bf16 v[16:19], v[184:187], v[160:163], 0
	v_mfma_f32_16x16x32_bf16 v[4:7], v[176:179], v[168:171], 0
	v_mfma_f32_16x16x32_bf16 v[0:3], v[184:187], v[168:171], 0
	v_mfma_f32_16x16x32_bf16 v[52:55], v[180:183], v[140:143], v[52:55]
	v_mfma_f32_16x16x32_bf16 v[48:51], v[200:203], v[140:143], v[48:51]
	v_mfma_f32_16x16x32_bf16 v[36:39], v[180:183], v[156:159], v[36:39]
	v_mfma_f32_16x16x32_bf16 v[32:35], v[200:203], v[156:159], v[32:35]
	v_mfma_f32_16x16x32_bf16 v[20:23], v[180:183], v[164:167], v[20:23]
	v_mfma_f32_16x16x32_bf16 v[16:19], v[200:203], v[164:167], v[16:19]
	v_mfma_f32_16x16x32_bf16 v[4:7], v[180:183], v[172:175], v[4:7]
	v_mfma_f32_16x16x32_bf16 v[0:3], v[200:203], v[172:175], v[0:3]
	v_add_u32_e32 v132, 0x18000, v236
	s_barrier
	ds_read_b128 v[120:123], v132
	ds_read_b128 v[124:127], v132 offset:1024
	ds_read_b128 v[128:131], v132 offset:2048
	ds_read_b128 v[132:135], v132 offset:3072
	ds_read_b128 v[136:139], v237 offset:32768
	ds_read_b128 v[140:143], v237 offset:33792
	ds_read_b128 v[152:155], v237 offset:34816
	ds_read_b128 v[156:159], v237 offset:35840
	ds_read_b128 v[160:163], v237 offset:36864
	ds_read_b128 v[164:167], v237 offset:37888
	ds_read_b128 v[168:171], v237 offset:38912
	ds_read_b128 v[172:175], v237 offset:39936
	s_add_u32 s48, s56, 0x160000
	s_addc_u32 s49, s57, 0
	s_mov_b32 m0, s34
	s_nop 0
	global_load_lds_dwordx4 v188, s[48:49]
	s_add_u32 s48, s56, 0x162000
	s_addc_u32 s49, s57, 0
	s_mov_b32 m0, s37
	s_nop 0
	global_load_lds_dwordx4 v188, s[48:49]
	s_waitcnt lgkmcnt(8)
	s_waitcnt vmcnt(10)
	s_barrier
	s_waitcnt lgkmcnt(7)
	v_mfma_f32_16x16x32_bf16 v[148:151], v[120:123], v[136:139], v[148:151]
	v_mfma_f32_16x16x32_bf16 v[144:147], v[128:131], v[136:139], v[144:147]
	s_waitcnt lgkmcnt(5)
	v_mfma_f32_16x16x32_bf16 v[108:111], v[120:123], v[152:155], v[108:111]
	v_mfma_f32_16x16x32_bf16 v[104:107], v[128:131], v[152:155], v[104:107]
	s_waitcnt lgkmcnt(3)
	v_mfma_f32_16x16x32_bf16 v[92:95], v[120:123], v[160:163], v[92:95]
	v_mfma_f32_16x16x32_bf16 v[88:91], v[128:131], v[160:163], v[88:91]
	s_waitcnt lgkmcnt(1)
	v_mfma_f32_16x16x32_bf16 v[76:79], v[120:123], v[168:171], v[76:79]
	v_mfma_f32_16x16x32_bf16 v[72:75], v[128:131], v[168:171], v[72:75]
	v_mfma_f32_16x16x32_bf16 v[148:151], v[124:127], v[140:143], v[148:151]
	v_mfma_f32_16x16x32_bf16 v[144:147], v[132:135], v[140:143], v[144:147]
	v_mfma_f32_16x16x32_bf16 v[108:111], v[124:127], v[156:159], v[108:111]
	v_mfma_f32_16x16x32_bf16 v[104:107], v[132:135], v[156:159], v[104:107]
	v_mfma_f32_16x16x32_bf16 v[92:95], v[124:127], v[164:167], v[92:95]
	v_mfma_f32_16x16x32_bf16 v[88:91], v[132:135], v[164:167], v[88:91]
	s_waitcnt lgkmcnt(0)
	v_mfma_f32_16x16x32_bf16 v[76:79], v[124:127], v[172:175], v[76:79]
	v_mfma_f32_16x16x32_bf16 v[72:75], v[132:135], v[172:175], v[72:75]
	s_barrier
	v_add_u32_e32 v200, 0x1c000, v236
	ds_read_b128 v[176:179], v200
	ds_read_b128 v[180:183], v200 offset:1024
	ds_read_b128 v[184:187], v200 offset:2048
	ds_read_b128 v[200:203], v200 offset:3072
	s_add_u32 s48, s60, 0x4000
	s_addc_u32 s49, s61, 0
	s_mov_b32 m0, s41
	s_nop 0
	global_load_lds_dwordx4 v188, s[48:49]
	s_add_u32 s48, s60, 0x6000
	s_addc_u32 s49, s61, 0
	s_mov_b32 m0, s42
	s_nop 0
	global_load_lds_dwordx4 v188, s[48:49]
	s_waitcnt vmcnt(10)
	s_barrier
; #define PG8_STAGE(bufoff, gbase, hoff, imm) do { _Pragma("unroll") for (int _i = 0; _i < 2; ++_i) { \
;         asm volatile("s_mov_b32 m0, %0\n\ts_nop 0\n\tglobal_load_lds_dwordx4 %1, %2" \
;             :: "s"(lds0 + (unsigned)((bufoff) + _i * 8192)), "v"(voff0), "s"((const char*)(gbase) + (size_t)(hoff) + (size_t)(_i * 8192)) : "memory"); } } while (0)
; #define PG8_LDA(dst, b, h) do { _Pragma("unroll") for (int m = 0; m < 4; ++m) _Pragma("unroll") for (int k = 0; k < 2; ++k) dst[m][k] = *(const LAS bf16x8*)(lds + PG8_SA(b, h) + aoff + m * 2048 + k * 1024); } while (0)
; #define PG8_LDB(dst, b, h) do { _Pragma("unroll") for (int n = 0; n < 2; ++n) _Pragma("unroll") for (int k = 0; k < 2; ++k) dst[n][k] = *(const LAS bf16x8*)(lds + PG8_SB(b, h) + boff + n * 2048 + k * 1024); } while (0)
; #define PG8_MMA(ai, bj, At, Bt) do { __builtin_amdgcn_s_setprio(1); _Pragma("unroll") for (int m = 0; m < 4; ++m) _Pragma("unroll") for (int n = 0; n < 2; ++n) _Pragma("unroll") for (int k = 0; k < 2; ++k) \
;         acc[ai][bj][m][n] = __builtin_amdgcn_mfma_f32_16x16x32_bf16(Bt[n][k], At[m][k], acc[ai][bj][m][n], 0, 0, 0); __builtin_amdgcn_s_setprio(0); } while (0)
; #define PG8_WAIT_V(n) asm volatile("s_waitcnt vmcnt(" #n ")" ::: "memory")
; #define PG8_WAIT_L(n) asm volatile("s_waitcnt lgkmcnt(" #n ")" ::: "memory")
; #define PG8_BAR __builtin_amdgcn_s_barrier()
; #define PG8_SCHED __builtin_amdgcn_sched_barrier(0)
; template <class Epi>
; __device__ __forceinline__ void gemm_phase(LAS unsigned char* lds, const Gemm g, const StaticOrder& S, const Epi& E) {
;     ...
;             PG8_LDB(B1, 1, 1); PG8_STAGE(PG8_SB(1, 0), b2 + KS, 0, 0);
;             PG8_BAR; PG8_WAIT_L(0); PG8_MMA(0, 1, At, B1); PG8_BAR;
;             PG8_LDA(At, 1, 1); PG8_STAGE(PG8_SA(1, 0), a2 + KS, 0, 0);
;             PG8_BAR; PG8_WAIT_L(0); PG8_MMA(1, 0, At, B0); PG8_BAR; PG8_SCHED;
;             PG8_STAGE(PG8_SB(1, 1), b2 + KS, hB, 0);
;             PG8_WAIT_V(6); PG8_BAR; PG8_MMA(1, 1, At, B1); PG8_BAR;
	s_waitcnt lgkmcnt(3)
	v_mfma_f32_16x16x32_bf16 v[116:119], v[176:179], v[136:139], v[116:119]
	s_waitcnt lgkmcnt(1)
	v_mfma_f32_16x16x32_bf16 v[112:115], v[184:187], v[136:139], v[112:115]
	v_mfma_f32_16x16x32_bf16 v[100:103], v[176:179], v[152:155], v[100:103]
	v_mfma_f32_16x16x32_bf16 v[96:99], v[184:187], v[152:155], v[96:99]
	v_mfma_f32_16x16x32_bf16 v[84:87], v[176:179], v[160:163], v[84:87]
	v_mfma_f32_16x16x32_bf16 v[80:83], v[184:187], v[160:163], v[80:83]
	v_mfma_f32_16x16x32_bf16 v[68:71], v[176:179], v[168:171], v[68:71]
	v_mfma_f32_16x16x32_bf16 v[64:67], v[184:187], v[168:171], v[64:67]
	v_mfma_f32_16x16x32_bf16 v[116:119], v[180:183], v[140:143], v[116:119]
	s_waitcnt lgkmcnt(0)
	v_mfma_f32_16x16x32_bf16 v[112:115], v[200:203], v[140:143], v[112:115]
	v_mfma_f32_16x16x32_bf16 v[100:103], v[180:183], v[156:159], v[100:103]
	v_mfma_f32_16x16x32_bf16 v[96:99], v[200:203], v[156:159], v[96:99]
	v_mfma_f32_16x16x32_bf16 v[84:87], v[180:183], v[164:167], v[84:87]
	v_mfma_f32_16x16x32_bf16 v[80:83], v[200:203], v[164:167], v[80:83]
	v_mfma_f32_16x16x32_bf16 v[68:71], v[180:183], v[172:175], v[68:71]
	v_mfma_f32_16x16x32_bf16 v[64:67], v[200:203], v[172:175], v[64:67]
	s_barrier
	ds_read_b128 v[136:139], v237 offset:49152
	ds_read_b128 v[140:143], v237 offset:50176
	ds_read_b128 v[152:155], v237 offset:51200
	ds_read_b128 v[156:159], v237 offset:52224
	ds_read_b128 v[160:163], v237 offset:53248
	ds_read_b128 v[164:167], v237 offset:54272
	ds_read_b128 v[168:171], v237 offset:55296
	ds_read_b128 v[172:175], v237 offset:56320
	s_add_u32 s48, s56, 0x4000
	s_addc_u32 s49, s57, 0
	s_mov_b32 m0, s43
	s_nop 0
	global_load_lds_dwordx4 v188, s[48:49]
	s_add_u32 s48, s56, 0x6000
	s_addc_u32 s49, s57, 0
	s_mov_b32 m0, s62
	s_nop 0
	global_load_lds_dwordx4 v188, s[48:49]
	s_barrier
	s_waitcnt lgkmcnt(7)
	v_mfma_f32_16x16x32_bf16 v[60:63], v[120:123], v[136:139], v[60:63]
	v_mfma_f32_16x16x32_bf16 v[56:59], v[128:131], v[136:139], v[56:59]
	s_waitcnt lgkmcnt(5)
	v_mfma_f32_16x16x32_bf16 v[44:47], v[120:123], v[152:155], v[44:47]
	v_mfma_f32_16x16x32_bf16 v[40:43], v[128:131], v[152:155], v[40:43]
	s_waitcnt lgkmcnt(3)
	v_mfma_f32_16x16x32_bf16 v[28:31], v[120:123], v[160:163], v[28:31]
	v_mfma_f32_16x16x32_bf16 v[24:27], v[128:131], v[160:163], v[24:27]
	s_waitcnt lgkmcnt(1)
	v_mfma_f32_16x16x32_bf16 v[12:15], v[120:123], v[168:171], v[12:15]
	v_mfma_f32_16x16x32_bf16 v[8:11], v[128:131], v[168:171], v[8:11]
	v_mfma_f32_16x16x32_bf16 v[60:63], v[124:127], v[140:143], v[60:63]
	v_mfma_f32_16x16x32_bf16 v[56:59], v[132:135], v[140:143], v[56:59]
	v_mfma_f32_16x16x32_bf16 v[44:47], v[124:127], v[156:159], v[44:47]
	v_mfma_f32_16x16x32_bf16 v[40:43], v[132:135], v[156:159], v[40:43]
	v_mfma_f32_16x16x32_bf16 v[28:31], v[124:127], v[164:167], v[28:31]
	v_mfma_f32_16x16x32_bf16 v[24:27], v[132:135], v[164:167], v[24:27]
	s_waitcnt lgkmcnt(0)
	v_mfma_f32_16x16x32_bf16 v[12:15], v[124:127], v[172:175], v[12:15]
	v_mfma_f32_16x16x32_bf16 v[8:11], v[132:135], v[172:175], v[8:11]
	s_barrier
	s_add_u32 s48, s60, 0x164000
	s_addc_u32 s49, s61, 0
	s_mov_b32 m0, s63
	s_nop 0
	global_load_lds_dwordx4 v188, s[48:49]
	s_add_u32 s48, s60, 0x166000
	s_addc_u32 s49, s61, 0
	s_mov_b32 m0, s64
	s_nop 0
	global_load_lds_dwordx4 v188, s[48:49]
	s_waitcnt vmcnt(10)
	s_barrier
	v_mfma_f32_16x16x32_bf16 v[52:55], v[176:179], v[136:139], v[52:55]
	v_mfma_f32_16x16x32_bf16 v[48:51], v[184:187], v[136:139], v[48:51]
	v_mfma_f32_16x16x32_bf16 v[36:39], v[176:179], v[152:155], v[36:39]
	v_mfma_f32_16x16x32_bf16 v[32:35], v[184:187], v[152:155], v[32:35]
	v_mfma_f32_16x16x32_bf16 v[20:23], v[176:179], v[160:163], v[20:23]
	v_mfma_f32_16x16x32_bf16 v[16:19], v[184:187], v[160:163], v[16:19]
	v_mfma_f32_16x16x32_bf16 v[4:7], v[176:179], v[168:171], v[4:7]
	v_mfma_f32_16x16x32_bf16 v[0:3], v[184:187], v[168:171], v[0:3]
	v_mfma_f32_16x16x32_bf16 v[52:55], v[180:183], v[140:143], v[52:55]
	v_mfma_f32_16x16x32_bf16 v[48:51], v[200:203], v[140:143], v[48:51]
	v_mfma_f32_16x16x32_bf16 v[36:39], v[180:183], v[156:159], v[36:39]
	v_mfma_f32_16x16x32_bf16 v[32:35], v[200:203], v[156:159], v[32:35]
	v_mfma_f32_16x16x32_bf16 v[20:23], v[180:183], v[164:167], v[20:23]
	v_mfma_f32_16x16x32_bf16 v[16:19], v[200:203], v[164:167], v[16:19]
	v_mfma_f32_16x16x32_bf16 v[4:7], v[180:183], v[172:175], v[4:7]
	v_mfma_f32_16x16x32_bf16 v[0:3], v[200:203], v[172:175], v[0:3]
	s_add_i32 s69, s69, 2
	s_add_u32 s0, s0, 0x8000
	s_addc_u32 s1, s1, 0
	s_cmpk_gt_u32 s69, 0x55
	s_mov_b64 s[56:57], s[58:59]
	s_barrier
